# attention v2: rpb table loads overlapped with first unit's K/Q loads, next unit's Q/K prefetched during PV, packed-f32 softmax, S-phase fragment double buffering
# speedup vs baseline: 1.0095x; 1.0035x over previous
.LBB0_674:
	s_movk_i32 s4, 0xe88
	v_cmp_gt_i32_e32 vcc, s4, v64
	s_waitcnt lgkmcnt(0)
	s_barrier
	s_mov_b64 exec, -1
	s_add_u32 s74, s50, 0x10200000
	s_addc_u32 s75, s51, 0
	s_cmpk_gt_i32 s2, 0x1ff
	s_cbranch_scc1 .LBB0_867
	s_load_dwordx2 s[96:97], s[0:1], 0x58
	s_load_dwordx2 s[78:79], s[0:1], 0x40
	v_lshl_add_u32 v0, s91, 6, v234
	v_and_b32_e32 v1, 15, v234
	v_lshrrev_b32_e32 v2, 4, v234
	s_movk_i32 s69, 0x88
	v_cmp_gt_u32_e64 s[80:81], s69, v0
	v_lshlrev_b32_e32 v226, 4, v0
	v_add_u32_e32 v227, 0x2000, v226
	v_lshrrev_b32_e32 v3, 4, v0
	v_mul_u32_u24_e32 v3, 0x110, v3
	v_and_b32_e32 v252, 15, v0
	v_lshl_add_u32 v228, v252, 4, v3
	v_lshrrev_b32_e32 v3, 3, v0
	v_and_b32_e32 v252, 7, v0
	v_lshlrev_b32_e32 v252, 4, v252
	v_lshl_add_u32 v229, v3, 14, v252
	v_add_u32_e32 v230, 0x100000, v229
	v_mul_u32_u24_e32 v3, 0x90, v3
	v_add_u32_e32 v231, v3, v252
	s_cmp_eq_u32 s92, 0
	s_cselect_b32 s29, 0, 8
	s_cmp_gt_u32 s92, 1
	s_cselect_b32 s29, 24, s29
	s_cmp_eq_u32 s92, 3
	s_cselect_b32 s29, 32, s29
	v_lshrrev_b32_e32 v3, 2, v1
	v_lshlrev_b32_e32 v3, 3, v3
	v_and_b32_e32 v252, 3, v1
	v_add3_u32 v3, v3, v252, s29
	v_mul_u32_u24_e32 v3, 0x110, v3
	v_lshl_add_u32 v232, v2, 4, v3
	v_mul_u32_u24_e32 v3, 0x90, v1
	v_lshl_add_u32 v252, v2, 3, s29
	v_lshl_add_u32 v233, v252, 1, v3
	v_lshlrev_b32_e32 v3, 8, v1
	v_lshl_add_u32 v235, v2, 4, v3
	v_lshlrev_b32_e32 v3, 12, v1
	v_lshl_add_u32 v236, v2, 3, v3
	v_lshlrev_b32_e32 v237, 4, v2
	v_xor_b32_e32 v238, 16, v234
	v_xor_b32_e32 v239, 32, v234
	v_lshlrev_b32_e32 v238, 2, v238
	v_lshlrev_b32_e32 v239, 2, v239
	v_lshl_add_u32 v3, s92, 4, v1
	v_subrev_u32_e32 v253, 8, v3
	v_max_i32_e32 v253, 0, v253
	v_min_i32_e32 v253, 48, v253
	v_add_u32_e32 v254, 16, v253
	v_add_u32_e32 v255, 0, v252
	v_cmp_ge_i32_e64 s[4:5], v255, v253
	v_cmp_lt_i32_e64 s[44:45], v255, v254
	v_sub_u32_e32 v255, v255, v3
	v_add_u32_e32 v255, 15, v255
	s_and_b64 s[4:5], s[4:5], s[44:45]
	v_max_i32_e32 v255, 0, v255
	v_min_i32_e32 v255, 30, v255
	v_lshlrev_b32_e32 v240, 2, v255
	v_add_u32_e32 v255, 1, v252
	v_cmp_ge_i32_e64 s[6:7], v255, v253
	v_cmp_lt_i32_e64 s[44:45], v255, v254
	v_sub_u32_e32 v255, v255, v3
	v_add_u32_e32 v255, 15, v255
	s_and_b64 s[6:7], s[6:7], s[44:45]
	v_max_i32_e32 v255, 0, v255
	v_min_i32_e32 v255, 30, v255
	v_lshlrev_b32_e32 v241, 2, v255
	v_add_u32_e32 v255, 2, v252
	v_cmp_ge_i32_e64 s[8:9], v255, v253
	v_cmp_lt_i32_e64 s[44:45], v255, v254
	v_sub_u32_e32 v255, v255, v3
	v_add_u32_e32 v255, 15, v255
	s_and_b64 s[8:9], s[8:9], s[44:45]
	v_max_i32_e32 v255, 0, v255
	v_min_i32_e32 v255, 30, v255
	v_lshlrev_b32_e32 v242, 2, v255
	v_add_u32_e32 v255, 3, v252
	v_cmp_ge_i32_e64 s[10:11], v255, v253
	v_cmp_lt_i32_e64 s[44:45], v255, v254
	v_sub_u32_e32 v255, v255, v3
	v_add_u32_e32 v255, 15, v255
	s_and_b64 s[10:11], s[10:11], s[44:45]
	v_max_i32_e32 v255, 0, v255
	v_min_i32_e32 v255, 30, v255
	v_lshlrev_b32_e32 v243, 2, v255
	v_add_u32_e32 v255, 4, v252
	v_cmp_ge_i32_e64 s[12:13], v255, v253
	v_cmp_lt_i32_e64 s[44:45], v255, v254
	v_sub_u32_e32 v255, v255, v3
	v_add_u32_e32 v255, 15, v255
	s_and_b64 s[12:13], s[12:13], s[44:45]
	v_max_i32_e32 v255, 0, v255
	v_min_i32_e32 v255, 30, v255
	v_lshlrev_b32_e32 v244, 2, v255
	v_add_u32_e32 v255, 5, v252
	v_cmp_ge_i32_e64 s[14:15], v255, v253
	v_cmp_lt_i32_e64 s[44:45], v255, v254
	v_sub_u32_e32 v255, v255, v3
	v_add_u32_e32 v255, 15, v255
	s_and_b64 s[14:15], s[14:15], s[44:45]
	v_max_i32_e32 v255, 0, v255
	v_min_i32_e32 v255, 30, v255
	v_lshlrev_b32_e32 v245, 2, v255
	v_add_u32_e32 v255, 6, v252
	v_cmp_ge_i32_e64 s[16:17], v255, v253
	v_cmp_lt_i32_e64 s[44:45], v255, v254
	v_sub_u32_e32 v255, v255, v3
	v_add_u32_e32 v255, 15, v255
	s_and_b64 s[16:17], s[16:17], s[44:45]
	v_max_i32_e32 v255, 0, v255
	v_min_i32_e32 v255, 30, v255
	v_lshlrev_b32_e32 v246, 2, v255
	v_add_u32_e32 v255, 7, v252
	v_cmp_ge_i32_e64 s[18:19], v255, v253
	v_cmp_lt_i32_e64 s[44:45], v255, v254
	v_sub_u32_e32 v255, v255, v3
	v_add_u32_e32 v255, 15, v255
	s_and_b64 s[18:19], s[18:19], s[44:45]
	v_max_i32_e32 v255, 0, v255
	v_min_i32_e32 v255, 30, v255
	v_lshlrev_b32_e32 v247, 2, v255
	v_lshlrev_b32_e32 v2, 2, v0
	s_mov_b32 s20, s2
	s_waitcnt lgkmcnt(0)
	global_load_dword v92, v2, s[78:79]
	s_add_u32 s78, s78, 0x800
	s_addc_u32 s79, s79, 0
	global_load_dword v93, v2, s[78:79]
	s_add_u32 s78, s78, 0x800
	s_addc_u32 s79, s79, 0
	global_load_dword v94, v2, s[78:79]
	s_add_u32 s78, s78, 0x800
	s_addc_u32 s79, s79, 0
	global_load_dword v95, v2, s[78:79]
	s_add_u32 s78, s78, 0x800
	s_addc_u32 s79, s79, 0
	global_load_dword v96, v2, s[78:79]
	s_add_u32 s78, s78, 0x800
	s_addc_u32 s79, s79, 0
	global_load_dword v97, v2, s[78:79]
	s_add_u32 s78, s78, 0x800
	s_addc_u32 s79, s79, 0
	global_load_dword v98, v2, s[78:79]
	s_add_u32 s78, s78, 0x800
	s_addc_u32 s79, s79, 0
	s_and_saveexec_b64 s[44:45], s[80:81]
	global_load_dword v99, v2, s[78:79]
	s_mov_b64 exec, s[44:45]
	s_and_b32 s69, s20, 7
	s_lshr_b32 s76, s20, 8
	s_lshl_b32 s69, s69, 1
	s_add_i32 s69, s69, s76
	s_lshl_b32 s69, s69, 12
	s_bfe_u32 s76, s20, 0x50003
	s_lshl_b32 s76, s76, 1
	s_add_i32 s77, s76, -4
	s_max_i32 s77, s77, 0
	s_min_i32 s77, s77, 56
	s_add_i32 s83, s76, -3
	s_max_i32 s83, s83, 0
	s_min_i32 s83, s83, 56
	s_add_i32 s83, s83, 8
	s_sub_i32 s83, s83, s77
	s_add_i32 s76, s76, s88
	s_lshl_b32 s77, s77, 6
	s_add_i32 s77, s77, s69
	s_lshl_b32 s77, s77, 8
	s_add_u32 s34, s50, s77
	s_addc_u32 s35, s51, 0
	s_add_u32 s34, s34, 0xe200000
	s_addc_u32 s35, s35, 0
	s_lshl_b32 s76, s76, 6
	s_add_i32 s76, s76, s69
	s_lshl_b32 s77, s92, 4
	s_add_i32 s76, s76, s77
	s_lshl_b32 s76, s76, 8
	s_add_u32 s36, s50, s76
	s_addc_u32 s37, s51, 0
	s_add_u32 s36, s36, 0xd200000
	s_addc_u32 s37, s37, 0
	global_load_dwordx4 v[76:79], v235, s[36:37] offset:0
	global_load_dwordx4 v[80:83], v235, s[36:37] offset:64
	global_load_dwordx4 v[84:87], v235, s[36:37] offset:128
	global_load_dwordx4 v[88:91], v235, s[36:37] offset:192
	global_load_dwordx4 v[4:7], v226, s[34:35]
	global_load_dwordx4 v[8:11], v227, s[34:35]
	s_add_u32 s34, s34, 0x4000
	s_addc_u32 s35, s35, 0
	global_load_dwordx4 v[12:15], v226, s[34:35]
	global_load_dwordx4 v[16:19], v227, s[34:35]
	s_add_u32 s34, s34, 0x4000
	s_addc_u32 s35, s35, 0
	global_load_dwordx4 v[20:23], v226, s[34:35]
	global_load_dwordx4 v[24:27], v227, s[34:35]
	s_add_u32 s34, s34, 0x4000
	s_addc_u32 s35, s35, 0
	global_load_dwordx4 v[28:31], v226, s[34:35]
	global_load_dwordx4 v[32:35], v227, s[34:35]
	s_add_u32 s34, s34, 0x4000
	s_addc_u32 s35, s35, 0
	global_load_dwordx4 v[36:39], v226, s[34:35]
	global_load_dwordx4 v[40:43], v227, s[34:35]
	s_add_u32 s34, s34, 0x4000
	s_addc_u32 s35, s35, 0
	global_load_dwordx4 v[44:47], v226, s[34:35]
	global_load_dwordx4 v[48:51], v227, s[34:35]
	s_add_u32 s34, s34, 0x4000
	s_addc_u32 s35, s35, 0
	global_load_dwordx4 v[52:55], v226, s[34:35]
	global_load_dwordx4 v[56:59], v227, s[34:35]
	s_add_u32 s34, s34, 0x4000
	s_addc_u32 s35, s35, 0
	global_load_dwordx4 v[60:63], v226, s[34:35]
	global_load_dwordx4 v[64:67], v227, s[34:35]
	s_add_u32 s34, s34, 0x4000
	s_addc_u32 s35, s35, 0
	s_cmp_lt_u32 s83, 9
	s_cbranch_scc1 .Latt_k8_skip_p
	global_load_dwordx4 v[68:71], v226, s[34:35]
	global_load_dwordx4 v[72:75], v227, s[34:35]
.Latt_k8_skip_p:
	s_and_b32 s30, s20, 7
	s_lshr_b32 s31, s20, 8
	s_lshl_b32 s30, s30, 1
	s_add_i32 s30, s30, s31
	s_lshr_b32 s21, s30, 3
	s_and_b32 s22, s30, 7
	s_bfe_u32 s23, s20, 0x50003
	s_lshl_b32 s24, s23, 1
	s_add_i32 s24, s24, s88
	s_lshl_b32 s31, s23, 1
	s_add_i32 s25, s31, -4
	s_max_i32 s25, s25, 0
	s_min_i32 s25, s25, 56
	s_add_i32 s26, s24, -4
	s_max_i32 s26, s26, 0
	s_min_i32 s26, s26, 56
	s_sub_i32 s27, s26, s25
	s_add_i32 s28, s31, -3
	s_max_i32 s28, s28, 0
	s_min_i32 s28, s28, 56
	s_add_i32 s28, s28, 8
	s_sub_i32 s28, s28, s25
	s_lshl_b32 s31, s22, 20
	s_lshl_b32 s30, s21, 12
	s_add_i32 s31, s31, s30
	s_lshl_b32 s30, s25, 6
	s_add_i32 s31, s31, s30
	s_lshl_b32 s31, s31, 1
	s_add_u32 s38, s50, s31
	s_addc_u32 s39, s51, 0
	s_add_u32 s38, s38, 0xf200000
	s_addc_u32 s39, s39, 0
	s_lshl_b32 s31, s21, 12
	s_lshl_b32 s30, s24, 6
	s_add_i32 s31, s31, s30
	s_lshl_b32 s30, s92, 4
	s_add_i32 s31, s31, s30
	s_lshl_b32 s31, s31, 11
	s_lshl_b32 s30, s22, 7
	s_add_i32 s31, s31, s30
	s_lshl_b32 s31, s31, 1
	s_add_u32 s40, s74, s31
	s_addc_u32 s41, s75, 0
	s_lshl_b32 s31, s22, 9
	s_add_u32 s60, s96, s31
	s_addc_u32 s61, s97, 0
	s_sub_i32 s31, s26, s24
	s_add_i32 s31, s31, 7
	s_mul_i32 s31, s31, 31
	s_mul_i32 s67, s22, 465
	s_add_i32 s67, s67, s31
	s_lshl_b32 s67, s67, 2
	s_waitcnt vmcnt(20)
	ds_write_b32 v2, v92 offset:0
	ds_write_b32 v2, v93 offset:2048
	ds_write_b32 v2, v94 offset:4096
	ds_write_b32 v2, v95 offset:6144
	ds_write_b32 v2, v96 offset:8192
	ds_write_b32 v2, v97 offset:10240
	ds_write_b32 v2, v98 offset:12288
	s_and_saveexec_b64 s[44:45], s[80:81]
	ds_write_b32 v2, v99 offset:14336
	s_mov_b64 exec, s[44:45]
	s_waitcnt vmcnt(14)
	v_add_u32_e32 v0, 0x3c00, v228
	ds_write_b128 v0, v[4:7]
	ds_write_b128 v0, v[8:11] offset:8704
	s_waitcnt vmcnt(12)
	v_add_u32_e32 v0, 0x8400, v228
	ds_write_b128 v0, v[12:15]
	ds_write_b128 v0, v[16:19] offset:8704
	s_waitcnt vmcnt(10)
	v_add_u32_e32 v0, 0xcc00, v228
	ds_write_b128 v0, v[20:23]
	ds_write_b128 v0, v[24:27] offset:8704
	s_waitcnt vmcnt(8)
	v_add_u32_e32 v0, 0x11400, v228
	ds_write_b128 v0, v[28:31]
	ds_write_b128 v0, v[32:35] offset:8704
	s_waitcnt vmcnt(6)
	v_add_u32_e32 v0, 0x15c00, v228
	ds_write_b128 v0, v[36:39]
	ds_write_b128 v0, v[40:43] offset:8704
	s_waitcnt vmcnt(4)
	v_add_u32_e32 v0, 0x1a400, v228
	ds_write_b128 v0, v[44:47]
	ds_write_b128 v0, v[48:51] offset:8704
	s_waitcnt vmcnt(2)
	v_add_u32_e32 v0, 0x1ec00, v228
	ds_write_b128 v0, v[52:55]
	ds_write_b128 v0, v[56:59] offset:8704
.Latt_unit:
	s_waitcnt lgkmcnt(0)
	s_barrier
	global_load_dwordx4 v[4:7], v229, s[38:39] offset:0
	global_load_dwordx4 v[8:11], v230, s[38:39] offset:0
	global_load_dwordx4 v[12:15], v229, s[38:39] offset:128
	global_load_dwordx4 v[16:19], v230, s[38:39] offset:128
	global_load_dwordx4 v[20:23], v229, s[38:39] offset:256
	global_load_dwordx4 v[24:27], v230, s[38:39] offset:256
	global_load_dwordx4 v[28:31], v229, s[38:39] offset:384
	global_load_dwordx4 v[32:35], v230, s[38:39] offset:384
	global_load_dwordx4 v[36:39], v229, s[38:39] offset:512
	global_load_dwordx4 v[40:43], v230, s[38:39] offset:512
	global_load_dwordx4 v[44:47], v229, s[38:39] offset:640
	global_load_dwordx4 v[48:51], v230, s[38:39] offset:640
	global_load_dwordx4 v[52:55], v229, s[38:39] offset:768
	global_load_dwordx4 v[56:59], v230, s[38:39] offset:768
	s_add_i32 s30, s27, 0
	s_add_i32 s31, s30, -7
	s_cmp_lt_i32 s30, 7
	s_cselect_b32 s30, s30, s31
	s_mul_i32 s30, s30, 0x4800
	s_add_i32 s30, s30, 0x3c00
	v_add_u32_e32 v0, s30, v232
	ds_read_b128 v[156:159], v0 offset:0
	ds_read_b128 v[172:175], v0 offset:1088
	ds_read_b128 v[160:163], v0 offset:64
	ds_read_b128 v[176:179], v0 offset:1152
	ds_read_b128 v[164:167], v0 offset:128
	ds_read_b128 v[180:183], v0 offset:1216
	ds_read_b128 v[168:171], v0 offset:192
	ds_read_b128 v[184:187], v0 offset:1280
	s_waitcnt lgkmcnt(0)
	s_add_i32 s30, s27, 1
	s_add_i32 s31, s30, -7
	s_cmp_lt_i32 s30, 7
	s_cselect_b32 s30, s30, s31
	s_mul_i32 s30, s30, 0x4800
	s_add_i32 s30, s30, 0x3c00
	v_add_u32_e32 v0, s30, v232
	ds_read_b128 v[188:191], v0 offset:0
	ds_read_b128 v[204:207], v0 offset:1088
	ds_read_b128 v[192:195], v0 offset:64
	ds_read_b128 v[208:211], v0 offset:1152
	ds_read_b128 v[196:199], v0 offset:128
	ds_read_b128 v[212:215], v0 offset:1216
	ds_read_b128 v[200:203], v0 offset:192
	ds_read_b128 v[216:219], v0 offset:1280
	v_mfma_f32_16x16x32_bf16 v[92:95], v[156:159], v[76:79], 0
	v_mfma_f32_16x16x32_bf16 v[96:99], v[172:175], v[76:79], 0
	v_mfma_f32_16x16x32_bf16 v[92:95], v[160:163], v[80:83], v[92:95]
	v_mfma_f32_16x16x32_bf16 v[96:99], v[176:179], v[80:83], v[96:99]
	v_mfma_f32_16x16x32_bf16 v[92:95], v[164:167], v[84:87], v[92:95]
	v_mfma_f32_16x16x32_bf16 v[96:99], v[180:183], v[84:87], v[96:99]
	v_mfma_f32_16x16x32_bf16 v[92:95], v[168:171], v[88:91], v[92:95]
	v_mfma_f32_16x16x32_bf16 v[96:99], v[184:187], v[88:91], v[96:99]
	s_waitcnt lgkmcnt(0)
	s_add_i32 s30, s27, 2
	s_add_i32 s31, s30, -7
	s_cmp_lt_i32 s30, 7
	s_cselect_b32 s30, s30, s31
	s_mul_i32 s30, s30, 0x4800
	s_add_i32 s30, s30, 0x3c00
	v_add_u32_e32 v0, s30, v232
	ds_read_b128 v[156:159], v0 offset:0
	ds_read_b128 v[172:175], v0 offset:1088
	ds_read_b128 v[160:163], v0 offset:64
	ds_read_b128 v[176:179], v0 offset:1152
	ds_read_b128 v[164:167], v0 offset:128
	ds_read_b128 v[180:183], v0 offset:1216
	ds_read_b128 v[168:171], v0 offset:192
	ds_read_b128 v[184:187], v0 offset:1280
	v_mfma_f32_16x16x32_bf16 v[100:103], v[188:191], v[76:79], 0
	v_mfma_f32_16x16x32_bf16 v[104:107], v[204:207], v[76:79], 0
	v_mfma_f32_16x16x32_bf16 v[100:103], v[192:195], v[80:83], v[100:103]
	v_mfma_f32_16x16x32_bf16 v[104:107], v[208:211], v[80:83], v[104:107]
	v_mfma_f32_16x16x32_bf16 v[100:103], v[196:199], v[84:87], v[100:103]
	v_mfma_f32_16x16x32_bf16 v[104:107], v[212:215], v[84:87], v[104:107]
	v_mfma_f32_16x16x32_bf16 v[100:103], v[200:203], v[88:91], v[100:103]
	v_mfma_f32_16x16x32_bf16 v[104:107], v[216:219], v[88:91], v[104:107]
	s_waitcnt lgkmcnt(0)
	s_add_i32 s30, s27, 3
	s_add_i32 s31, s30, -7
	s_cmp_lt_i32 s30, 7
	s_cselect_b32 s30, s30, s31
	s_mul_i32 s30, s30, 0x4800
	s_add_i32 s30, s30, 0x3c00
	v_add_u32_e32 v0, s30, v232
	ds_read_b128 v[188:191], v0 offset:0
	ds_read_b128 v[204:207], v0 offset:1088
	ds_read_b128 v[192:195], v0 offset:64
	ds_read_b128 v[208:211], v0 offset:1152
	ds_read_b128 v[196:199], v0 offset:128
	ds_read_b128 v[212:215], v0 offset:1216
	ds_read_b128 v[200:203], v0 offset:192
	ds_read_b128 v[216:219], v0 offset:1280
	v_mfma_f32_16x16x32_bf16 v[108:111], v[156:159], v[76:79], 0
	v_mfma_f32_16x16x32_bf16 v[112:115], v[172:175], v[76:79], 0
	v_mfma_f32_16x16x32_bf16 v[108:111], v[160:163], v[80:83], v[108:111]
	v_mfma_f32_16x16x32_bf16 v[112:115], v[176:179], v[80:83], v[112:115]
	v_mfma_f32_16x16x32_bf16 v[108:111], v[164:167], v[84:87], v[108:111]
	v_mfma_f32_16x16x32_bf16 v[112:115], v[180:183], v[84:87], v[112:115]
	v_mfma_f32_16x16x32_bf16 v[108:111], v[168:171], v[88:91], v[108:111]
	v_mfma_f32_16x16x32_bf16 v[112:115], v[184:187], v[88:91], v[112:115]
	s_waitcnt lgkmcnt(0)
	s_add_i32 s30, s27, 4
	s_add_i32 s31, s30, -7
	s_cmp_lt_i32 s30, 7
	s_cselect_b32 s30, s30, s31
	s_mul_i32 s30, s30, 0x4800
	s_add_i32 s30, s30, 0x3c00
	v_add_u32_e32 v0, s30, v232
	ds_read_b128 v[156:159], v0 offset:0
	ds_read_b128 v[172:175], v0 offset:1088
	ds_read_b128 v[160:163], v0 offset:64
	ds_read_b128 v[176:179], v0 offset:1152
	ds_read_b128 v[164:167], v0 offset:128
	ds_read_b128 v[180:183], v0 offset:1216
	ds_read_b128 v[168:171], v0 offset:192
	ds_read_b128 v[184:187], v0 offset:1280
	v_mfma_f32_16x16x32_bf16 v[116:119], v[188:191], v[76:79], 0
	v_mfma_f32_16x16x32_bf16 v[120:123], v[204:207], v[76:79], 0
	v_mfma_f32_16x16x32_bf16 v[116:119], v[192:195], v[80:83], v[116:119]
	v_mfma_f32_16x16x32_bf16 v[120:123], v[208:211], v[80:83], v[120:123]
	v_mfma_f32_16x16x32_bf16 v[116:119], v[196:199], v[84:87], v[116:119]
	v_mfma_f32_16x16x32_bf16 v[120:123], v[212:215], v[84:87], v[120:123]
	v_mfma_f32_16x16x32_bf16 v[116:119], v[200:203], v[88:91], v[116:119]
	v_mfma_f32_16x16x32_bf16 v[120:123], v[216:219], v[88:91], v[120:123]
	s_waitcnt lgkmcnt(0)
	s_add_i32 s30, s27, 5
	s_add_i32 s31, s30, -7
	s_cmp_lt_i32 s30, 7
	s_cselect_b32 s30, s30, s31
	s_mul_i32 s30, s30, 0x4800
	s_add_i32 s30, s30, 0x3c00
	v_add_u32_e32 v0, s30, v232
	ds_read_b128 v[188:191], v0 offset:0
	ds_read_b128 v[204:207], v0 offset:1088
	ds_read_b128 v[192:195], v0 offset:64
	ds_read_b128 v[208:211], v0 offset:1152
	ds_read_b128 v[196:199], v0 offset:128
	ds_read_b128 v[212:215], v0 offset:1216
	ds_read_b128 v[200:203], v0 offset:192
	ds_read_b128 v[216:219], v0 offset:1280
	v_mfma_f32_16x16x32_bf16 v[124:127], v[156:159], v[76:79], 0
	v_mfma_f32_16x16x32_bf16 v[128:131], v[172:175], v[76:79], 0
	v_mfma_f32_16x16x32_bf16 v[124:127], v[160:163], v[80:83], v[124:127]
	v_mfma_f32_16x16x32_bf16 v[128:131], v[176:179], v[80:83], v[128:131]
	v_mfma_f32_16x16x32_bf16 v[124:127], v[164:167], v[84:87], v[124:127]
	v_mfma_f32_16x16x32_bf16 v[128:131], v[180:183], v[84:87], v[128:131]
	v_mfma_f32_16x16x32_bf16 v[124:127], v[168:171], v[88:91], v[124:127]
	v_mfma_f32_16x16x32_bf16 v[128:131], v[184:187], v[88:91], v[128:131]
	s_waitcnt lgkmcnt(0)
	s_cmp_lg_u32 s27, 0
	s_cbranch_scc1 .Latt_s6a_skip
	s_add_i32 s30, s27, 6
	s_add_i32 s31, s30, -7
	s_cmp_lt_i32 s30, 7
	s_cselect_b32 s30, s30, s31
	s_mul_i32 s30, s30, 0x4800
	s_add_i32 s30, s30, 0x3c00
	v_add_u32_e32 v0, s30, v232
	ds_read_b128 v[156:159], v0 offset:0
	ds_read_b128 v[172:175], v0 offset:1088
	ds_read_b128 v[160:163], v0 offset:64
	ds_read_b128 v[176:179], v0 offset:1152
	ds_read_b128 v[164:167], v0 offset:128
	ds_read_b128 v[180:183], v0 offset:1216
	ds_read_b128 v[168:171], v0 offset:192
	ds_read_b128 v[184:187], v0 offset:1280
	v_mfma_f32_16x16x32_bf16 v[132:135], v[188:191], v[76:79], 0
	v_mfma_f32_16x16x32_bf16 v[136:139], v[204:207], v[76:79], 0
	v_mfma_f32_16x16x32_bf16 v[132:135], v[192:195], v[80:83], v[132:135]
	v_mfma_f32_16x16x32_bf16 v[136:139], v[208:211], v[80:83], v[136:139]
	v_mfma_f32_16x16x32_bf16 v[132:135], v[196:199], v[84:87], v[132:135]
	v_mfma_f32_16x16x32_bf16 v[136:139], v[212:215], v[84:87], v[136:139]
	v_mfma_f32_16x16x32_bf16 v[132:135], v[200:203], v[88:91], v[132:135]
	v_mfma_f32_16x16x32_bf16 v[136:139], v[216:219], v[88:91], v[136:139]
	s_waitcnt lgkmcnt(0)
	v_mfma_f32_16x16x32_bf16 v[140:143], v[156:159], v[76:79], 0
	v_mfma_f32_16x16x32_bf16 v[144:147], v[172:175], v[76:79], 0
	v_mfma_f32_16x16x32_bf16 v[140:143], v[160:163], v[80:83], v[140:143]
	v_mfma_f32_16x16x32_bf16 v[144:147], v[176:179], v[80:83], v[144:147]
	v_mfma_f32_16x16x32_bf16 v[140:143], v[164:167], v[84:87], v[140:143]
	v_mfma_f32_16x16x32_bf16 v[144:147], v[180:183], v[84:87], v[144:147]
	v_mfma_f32_16x16x32_bf16 v[140:143], v[168:171], v[88:91], v[140:143]
	v_mfma_f32_16x16x32_bf16 v[144:147], v[184:187], v[88:91], v[144:147]
	s_branch .Latt_s6a_done
.Latt_s6a_skip:
	v_mfma_f32_16x16x32_bf16 v[132:135], v[188:191], v[76:79], 0
	v_mfma_f32_16x16x32_bf16 v[136:139], v[204:207], v[76:79], 0
	v_mfma_f32_16x16x32_bf16 v[132:135], v[192:195], v[80:83], v[132:135]
	v_mfma_f32_16x16x32_bf16 v[136:139], v[208:211], v[80:83], v[136:139]
	v_mfma_f32_16x16x32_bf16 v[132:135], v[196:199], v[84:87], v[132:135]
	v_mfma_f32_16x16x32_bf16 v[136:139], v[212:215], v[84:87], v[136:139]
	v_mfma_f32_16x16x32_bf16 v[132:135], v[200:203], v[88:91], v[132:135]
	v_mfma_f32_16x16x32_bf16 v[136:139], v[216:219], v[88:91], v[136:139]

.Latt_v8_skip:
	s_cmp_eq_u32 s27, 0
	s_cbranch_scc1 .Latt_s6b_skip
	s_add_i32 s30, s27, 6
	s_add_i32 s31, s30, -7
	s_cmp_lt_i32 s30, 7
	s_cselect_b32 s30, s30, s31
	s_mul_i32 s30, s30, 0x4800
	s_add_i32 s30, s30, 0x3c00
	v_add_u32_e32 v0, s30, v232
	ds_read_b128 v[156:159], v0 offset:0
	ds_read_b128 v[172:175], v0 offset:1088
	ds_read_b128 v[160:163], v0 offset:64
	ds_read_b128 v[176:179], v0 offset:1152
	ds_read_b128 v[164:167], v0 offset:128
	ds_read_b128 v[180:183], v0 offset:1216
	ds_read_b128 v[168:171], v0 offset:192
	ds_read_b128 v[184:187], v0 offset:1280
	s_waitcnt lgkmcnt(0)
	s_add_i32 s30, s27, 7
	s_add_i32 s31, s30, -7
	s_cmp_lt_i32 s30, 7
	s_cselect_b32 s30, s30, s31
	s_mul_i32 s30, s30, 0x4800
	s_add_i32 s30, s30, 0x3c00
	v_add_u32_e32 v0, s30, v232
	ds_read_b128 v[188:191], v0 offset:0
	ds_read_b128 v[204:207], v0 offset:1088
	ds_read_b128 v[192:195], v0 offset:64
	ds_read_b128 v[208:211], v0 offset:1152
	ds_read_b128 v[196:199], v0 offset:128
	ds_read_b128 v[212:215], v0 offset:1216
	ds_read_b128 v[200:203], v0 offset:192
	ds_read_b128 v[216:219], v0 offset:1280
	v_mfma_f32_16x16x32_bf16 v[140:143], v[156:159], v[76:79], 0
	v_mfma_f32_16x16x32_bf16 v[144:147], v[172:175], v[76:79], 0
	v_mfma_f32_16x16x32_bf16 v[140:143], v[160:163], v[80:83], v[140:143]
	v_mfma_f32_16x16x32_bf16 v[144:147], v[176:179], v[80:83], v[144:147]
	v_mfma_f32_16x16x32_bf16 v[140:143], v[164:167], v[84:87], v[140:143]
	v_mfma_f32_16x16x32_bf16 v[144:147], v[180:183], v[84:87], v[144:147]
	v_mfma_f32_16x16x32_bf16 v[140:143], v[168:171], v[88:91], v[140:143]
	v_mfma_f32_16x16x32_bf16 v[144:147], v[184:187], v[88:91], v[144:147]
	s_waitcnt lgkmcnt(0)
	v_mfma_f32_16x16x32_bf16 v[148:151], v[188:191], v[76:79], 0
	v_mfma_f32_16x16x32_bf16 v[152:155], v[204:207], v[76:79], 0
	v_mfma_f32_16x16x32_bf16 v[148:151], v[192:195], v[80:83], v[148:151]
	v_mfma_f32_16x16x32_bf16 v[152:155], v[208:211], v[80:83], v[152:155]
	v_mfma_f32_16x16x32_bf16 v[148:151], v[196:199], v[84:87], v[148:151]
	v_mfma_f32_16x16x32_bf16 v[152:155], v[212:215], v[84:87], v[152:155]
	v_mfma_f32_16x16x32_bf16 v[148:151], v[200:203], v[88:91], v[148:151]
	v_mfma_f32_16x16x32_bf16 v[152:155], v[216:219], v[88:91], v[152:155]
	s_branch .Latt_s6b_done
.Latt_s6b_skip:
	s_add_i32 s30, s27, 7
	s_add_i32 s31, s30, -7
	s_cmp_lt_i32 s30, 7
	s_cselect_b32 s30, s30, s31
	s_mul_i32 s30, s30, 0x4800
	s_add_i32 s30, s30, 0x3c00
	v_add_u32_e32 v0, s30, v232
	ds_read_b128 v[188:191], v0 offset:0
	ds_read_b128 v[204:207], v0 offset:1088
	ds_read_b128 v[192:195], v0 offset:64
	ds_read_b128 v[208:211], v0 offset:1152
	ds_read_b128 v[196:199], v0 offset:128
	ds_read_b128 v[212:215], v0 offset:1216
	ds_read_b128 v[200:203], v0 offset:192
	ds_read_b128 v[216:219], v0 offset:1280
	s_waitcnt lgkmcnt(0)
	v_mfma_f32_16x16x32_bf16 v[148:151], v[188:191], v[76:79], 0
	v_mfma_f32_16x16x32_bf16 v[152:155], v[204:207], v[76:79], 0
	v_mfma_f32_16x16x32_bf16 v[148:151], v[192:195], v[80:83], v[148:151]
	v_mfma_f32_16x16x32_bf16 v[152:155], v[208:211], v[80:83], v[152:155]
	v_mfma_f32_16x16x32_bf16 v[148:151], v[196:199], v[84:87], v[148:151]
	v_mfma_f32_16x16x32_bf16 v[152:155], v[212:215], v[84:87], v[152:155]
	v_mfma_f32_16x16x32_bf16 v[148:151], v[200:203], v[88:91], v[148:151]
	v_mfma_f32_16x16x32_bf16 v[152:155], v[216:219], v[88:91], v[152:155]
.Latt_s6b_done:
	s_barrier
	s_cmp_lt_u32 s28, 9
	s_cbranch_scc1 .Latt_vw_n8
	s_waitcnt vmcnt(4)
	s_branch .Latt_vw_go

.Latt_vw_go:
	v_add_u32_e32 v0, 0x3c00, v231
	ds_write_b128 v0, v[4:7]
	ds_write_b128 v0, v[8:11] offset:9216
	v_add_u32_e32 v0, 0x8400, v231
	ds_write_b128 v0, v[12:15]
	ds_write_b128 v0, v[16:19] offset:9216
	v_add_u32_e32 v0, 0xcc00, v231
	ds_write_b128 v0, v[20:23]
	ds_write_b128 v0, v[24:27] offset:9216
	v_add_u32_e32 v0, 0x11400, v231
	ds_write_b128 v0, v[28:31]
	ds_write_b128 v0, v[32:35] offset:9216
	v_add_u32_e32 v0, 0x15c00, v231
	ds_write_b128 v0, v[36:39]
	ds_write_b128 v0, v[40:43] offset:9216
	v_add_u32_e32 v0, 0x1a400, v231
	ds_write_b128 v0, v[44:47]
	ds_write_b128 v0, v[48:51] offset:9216
	v_add_u32_e32 v0, 0x1ec00, v231
	ds_write_b128 v0, v[52:55]
	ds_write_b128 v0, v[56:59] offset:9216
	v_mov_b32_e32 v251, 0xf149f2ca
	v_mov_b32_e32 v252, 0x3db504f3
	v_mov_b32_e32 v254, 0x3fb8aa3b
	v_add_u32_e32 v156, s67, v240
	v_add_u32_e32 v157, s67, v241
	v_add_u32_e32 v158, s67, v242
	v_add_u32_e32 v159, s67, v243
	v_add_u32_e32 v160, s67, v244
	v_add_u32_e32 v161, s67, v245
	v_add_u32_e32 v162, s67, v246
	v_add_u32_e32 v163, s67, v247
	v_mov_b32_e32 v248, 0xff61b1e6
	ds_read_b32 v164, v156 offset:0
	ds_read_b32 v165, v157 offset:0
	ds_read_b32 v166, v158 offset:0
	ds_read_b32 v167, v159 offset:0
	ds_read_b32 v168, v160 offset:0
	ds_read_b32 v169, v161 offset:0
	ds_read_b32 v170, v162 offset:0
	ds_read_b32 v171, v163 offset:0
	s_waitcnt lgkmcnt(0)
	ds_read_b32 v172, v156 offset:124
	ds_read_b32 v173, v157 offset:124
	ds_read_b32 v174, v158 offset:124
	ds_read_b32 v175, v159 offset:124
	ds_read_b32 v176, v160 offset:124
	ds_read_b32 v177, v161 offset:124
	ds_read_b32 v178, v162 offset:124
	ds_read_b32 v179, v163 offset:124
	v_pk_fma_f32 v[92:93], v[92:93], v[252:253], v[164:165] op_sel_hi:[1,0,1]
	v_pk_fma_f32 v[94:95], v[94:95], v[252:253], v[166:167] op_sel_hi:[1,0,1]
	v_pk_fma_f32 v[96:97], v[96:97], v[252:253], v[168:169] op_sel_hi:[1,0,1]
	v_pk_fma_f32 v[98:99], v[98:99], v[252:253], v[170:171] op_sel_hi:[1,0,1]
	v_cndmask_b32_e64 v92, v251, v92, s[4:5]
	v_cndmask_b32_e64 v93, v251, v93, s[6:7]
	v_cndmask_b32_e64 v94, v251, v94, s[8:9]
	v_cndmask_b32_e64 v95, v251, v95, s[10:11]
	v_cndmask_b32_e64 v96, v251, v96, s[12:13]
	v_cndmask_b32_e64 v97, v251, v97, s[14:15]
	v_cndmask_b32_e64 v98, v251, v98, s[16:17]
	v_cndmask_b32_e64 v99, v251, v99, s[18:19]
	v_max3_f32 v248, v248, v92, v93
	v_max3_f32 v248, v248, v94, v95
	v_max3_f32 v248, v248, v96, v97
	v_max3_f32 v248, v248, v98, v99
	s_waitcnt lgkmcnt(0)
	ds_read_b32 v164, v156 offset:248
	ds_read_b32 v165, v157 offset:248
	ds_read_b32 v166, v158 offset:248
	ds_read_b32 v167, v159 offset:248
	ds_read_b32 v168, v160 offset:248
	ds_read_b32 v169, v161 offset:248
	ds_read_b32 v170, v162 offset:248
	ds_read_b32 v171, v163 offset:248
	v_pk_fma_f32 v[100:101], v[100:101], v[252:253], v[172:173] op_sel_hi:[1,0,1]
	v_pk_fma_f32 v[102:103], v[102:103], v[252:253], v[174:175] op_sel_hi:[1,0,1]
	v_pk_fma_f32 v[104:105], v[104:105], v[252:253], v[176:177] op_sel_hi:[1,0,1]
	v_pk_fma_f32 v[106:107], v[106:107], v[252:253], v[178:179] op_sel_hi:[1,0,1]
	v_cndmask_b32_e64 v100, v251, v100, s[4:5]
	v_cndmask_b32_e64 v101, v251, v101, s[6:7]
	v_cndmask_b32_e64 v102, v251, v102, s[8:9]
	v_cndmask_b32_e64 v103, v251, v103, s[10:11]
	v_cndmask_b32_e64 v104, v251, v104, s[12:13]
	v_cndmask_b32_e64 v105, v251, v105, s[14:15]
	v_cndmask_b32_e64 v106, v251, v106, s[16:17]
	v_cndmask_b32_e64 v107, v251, v107, s[18:19]
	v_max3_f32 v248, v248, v100, v101
	v_max3_f32 v248, v248, v102, v103
	v_max3_f32 v248, v248, v104, v105
	v_max3_f32 v248, v248, v106, v107
	s_waitcnt lgkmcnt(0)
	ds_read_b32 v172, v156 offset:372
	ds_read_b32 v173, v157 offset:372
	ds_read_b32 v174, v158 offset:372
	ds_read_b32 v175, v159 offset:372
	ds_read_b32 v176, v160 offset:372
	ds_read_b32 v177, v161 offset:372
	ds_read_b32 v178, v162 offset:372
	ds_read_b32 v179, v163 offset:372
	v_pk_fma_f32 v[108:109], v[108:109], v[252:253], v[164:165] op_sel_hi:[1,0,1]
	v_pk_fma_f32 v[110:111], v[110:111], v[252:253], v[166:167] op_sel_hi:[1,0,1]
	v_pk_fma_f32 v[112:113], v[112:113], v[252:253], v[168:169] op_sel_hi:[1,0,1]
	v_pk_fma_f32 v[114:115], v[114:115], v[252:253], v[170:171] op_sel_hi:[1,0,1]
	v_cndmask_b32_e64 v108, v251, v108, s[4:5]
	v_cndmask_b32_e64 v109, v251, v109, s[6:7]
	v_cndmask_b32_e64 v110, v251, v110, s[8:9]
	v_cndmask_b32_e64 v111, v251, v111, s[10:11]
	v_cndmask_b32_e64 v112, v251, v112, s[12:13]
	v_cndmask_b32_e64 v113, v251, v113, s[14:15]
	v_cndmask_b32_e64 v114, v251, v114, s[16:17]
	v_cndmask_b32_e64 v115, v251, v115, s[18:19]
	v_max3_f32 v248, v248, v108, v109
	v_max3_f32 v248, v248, v110, v111
	v_max3_f32 v248, v248, v112, v113
	v_max3_f32 v248, v248, v114, v115
	s_waitcnt lgkmcnt(0)
	ds_read_b32 v164, v156 offset:496
	ds_read_b32 v165, v157 offset:496
	ds_read_b32 v166, v158 offset:496
	ds_read_b32 v167, v159 offset:496
	ds_read_b32 v168, v160 offset:496
	ds_read_b32 v169, v161 offset:496
	ds_read_b32 v170, v162 offset:496
	ds_read_b32 v171, v163 offset:496
	v_pk_fma_f32 v[116:117], v[116:117], v[252:253], v[172:173] op_sel_hi:[1,0,1]
	v_pk_fma_f32 v[118:119], v[118:119], v[252:253], v[174:175] op_sel_hi:[1,0,1]
	v_pk_fma_f32 v[120:121], v[120:121], v[252:253], v[176:177] op_sel_hi:[1,0,1]
	v_pk_fma_f32 v[122:123], v[122:123], v[252:253], v[178:179] op_sel_hi:[1,0,1]
	v_cndmask_b32_e64 v116, v251, v116, s[4:5]
	v_cndmask_b32_e64 v117, v251, v117, s[6:7]
	v_cndmask_b32_e64 v118, v251, v118, s[8:9]
	v_cndmask_b32_e64 v119, v251, v119, s[10:11]
	v_cndmask_b32_e64 v120, v251, v120, s[12:13]
	v_cndmask_b32_e64 v121, v251, v121, s[14:15]
	v_cndmask_b32_e64 v122, v251, v122, s[16:17]
	v_cndmask_b32_e64 v123, v251, v123, s[18:19]
	v_max3_f32 v248, v248, v116, v117
	v_max3_f32 v248, v248, v118, v119
	v_max3_f32 v248, v248, v120, v121
	v_max3_f32 v248, v248, v122, v123
	s_waitcnt lgkmcnt(0)
	ds_read_b32 v172, v156 offset:620
	ds_read_b32 v173, v157 offset:620
	ds_read_b32 v174, v158 offset:620
	ds_read_b32 v175, v159 offset:620
	ds_read_b32 v176, v160 offset:620
	ds_read_b32 v177, v161 offset:620
	ds_read_b32 v178, v162 offset:620
	ds_read_b32 v179, v163 offset:620
	v_pk_fma_f32 v[124:125], v[124:125], v[252:253], v[164:165] op_sel_hi:[1,0,1]
	v_pk_fma_f32 v[126:127], v[126:127], v[252:253], v[166:167] op_sel_hi:[1,0,1]
	v_pk_fma_f32 v[128:129], v[128:129], v[252:253], v[168:169] op_sel_hi:[1,0,1]
	v_pk_fma_f32 v[130:131], v[130:131], v[252:253], v[170:171] op_sel_hi:[1,0,1]
	v_cndmask_b32_e64 v124, v251, v124, s[4:5]
	v_cndmask_b32_e64 v125, v251, v125, s[6:7]
	v_cndmask_b32_e64 v126, v251, v126, s[8:9]
	v_cndmask_b32_e64 v127, v251, v127, s[10:11]
	v_cndmask_b32_e64 v128, v251, v128, s[12:13]
	v_cndmask_b32_e64 v129, v251, v129, s[14:15]
	v_cndmask_b32_e64 v130, v251, v130, s[16:17]
	v_cndmask_b32_e64 v131, v251, v131, s[18:19]
	v_max3_f32 v248, v248, v124, v125
	v_max3_f32 v248, v248, v126, v127
	v_max3_f32 v248, v248, v128, v129
	v_max3_f32 v248, v248, v130, v131
	s_waitcnt lgkmcnt(0)
	ds_read_b32 v164, v156 offset:744
	ds_read_b32 v165, v157 offset:744
	ds_read_b32 v166, v158 offset:744
	ds_read_b32 v167, v159 offset:744
	ds_read_b32 v168, v160 offset:744
	ds_read_b32 v169, v161 offset:744
	ds_read_b32 v170, v162 offset:744
	ds_read_b32 v171, v163 offset:744
	v_pk_fma_f32 v[132:133], v[132:133], v[252:253], v[172:173] op_sel_hi:[1,0,1]
	v_pk_fma_f32 v[134:135], v[134:135], v[252:253], v[174:175] op_sel_hi:[1,0,1]
	v_pk_fma_f32 v[136:137], v[136:137], v[252:253], v[176:177] op_sel_hi:[1,0,1]
	v_pk_fma_f32 v[138:139], v[138:139], v[252:253], v[178:179] op_sel_hi:[1,0,1]
	v_cndmask_b32_e64 v132, v251, v132, s[4:5]
	v_cndmask_b32_e64 v133, v251, v133, s[6:7]
	v_cndmask_b32_e64 v134, v251, v134, s[8:9]
	v_cndmask_b32_e64 v135, v251, v135, s[10:11]
	v_cndmask_b32_e64 v136, v251, v136, s[12:13]
	v_cndmask_b32_e64 v137, v251, v137, s[14:15]
	v_cndmask_b32_e64 v138, v251, v138, s[16:17]
	v_cndmask_b32_e64 v139, v251, v139, s[18:19]
	v_max3_f32 v248, v248, v132, v133
	v_max3_f32 v248, v248, v134, v135
	v_max3_f32 v248, v248, v136, v137
	v_max3_f32 v248, v248, v138, v139
	s_waitcnt lgkmcnt(0)
	ds_read_b32 v172, v156 offset:868
	ds_read_b32 v173, v157 offset:868
	ds_read_b32 v174, v158 offset:868
	ds_read_b32 v175, v159 offset:868
	ds_read_b32 v176, v160 offset:868
	ds_read_b32 v177, v161 offset:868
	ds_read_b32 v178, v162 offset:868
	ds_read_b32 v179, v163 offset:868
	v_pk_fma_f32 v[140:141], v[140:141], v[252:253], v[164:165] op_sel_hi:[1,0,1]
	v_pk_fma_f32 v[142:143], v[142:143], v[252:253], v[166:167] op_sel_hi:[1,0,1]
	v_pk_fma_f32 v[144:145], v[144:145], v[252:253], v[168:169] op_sel_hi:[1,0,1]
	v_pk_fma_f32 v[146:147], v[146:147], v[252:253], v[170:171] op_sel_hi:[1,0,1]
	v_cndmask_b32_e64 v140, v251, v140, s[4:5]
	v_cndmask_b32_e64 v141, v251, v141, s[6:7]
	v_cndmask_b32_e64 v142, v251, v142, s[8:9]
	v_cndmask_b32_e64 v143, v251, v143, s[10:11]
	v_cndmask_b32_e64 v144, v251, v144, s[12:13]
	v_cndmask_b32_e64 v145, v251, v145, s[14:15]
	v_cndmask_b32_e64 v146, v251, v146, s[16:17]
	v_cndmask_b32_e64 v147, v251, v147, s[18:19]
	v_max3_f32 v248, v248, v140, v141
	v_max3_f32 v248, v248, v142, v143
	v_max3_f32 v248, v248, v144, v145
	v_max3_f32 v248, v248, v146, v147
	s_waitcnt lgkmcnt(0)
	v_pk_fma_f32 v[148:149], v[148:149], v[252:253], v[172:173] op_sel_hi:[1,0,1]
	v_pk_fma_f32 v[150:151], v[150:151], v[252:253], v[174:175] op_sel_hi:[1,0,1]
	v_pk_fma_f32 v[152:153], v[152:153], v[252:253], v[176:177] op_sel_hi:[1,0,1]
	v_pk_fma_f32 v[154:155], v[154:155], v[252:253], v[178:179] op_sel_hi:[1,0,1]
	v_cndmask_b32_e64 v148, v251, v148, s[4:5]
	v_cndmask_b32_e64 v149, v251, v149, s[6:7]
	v_cndmask_b32_e64 v150, v251, v150, s[8:9]
	v_cndmask_b32_e64 v151, v251, v151, s[10:11]
	v_cndmask_b32_e64 v152, v251, v152, s[12:13]
	v_cndmask_b32_e64 v153, v251, v153, s[14:15]
	v_cndmask_b32_e64 v154, v251, v154, s[16:17]
	v_cndmask_b32_e64 v155, v251, v155, s[18:19]
	v_max3_f32 v248, v248, v148, v149
	v_max3_f32 v248, v248, v150, v151
	v_max3_f32 v248, v248, v152, v153
	v_max3_f32 v248, v248, v154, v155
	ds_bpermute_b32 v0, v238, v248
	s_waitcnt lgkmcnt(0)
	v_max_f32_e32 v248, v248, v0
	ds_bpermute_b32 v0, v239, v248
	s_waitcnt lgkmcnt(0)
	v_max_f32_e32 v248, v248, v0
	v_mov_b32_e32 v2, 0
	v_mov_b32_e32 v3, 0
	v_pk_add_f32 v[92:93], v[92:93], v[248:249] op_sel_hi:[1,0] neg_lo:[0,1] neg_hi:[0,1]
	v_pk_add_f32 v[94:95], v[94:95], v[248:249] op_sel_hi:[1,0] neg_lo:[0,1] neg_hi:[0,1]
	v_pk_add_f32 v[96:97], v[96:97], v[248:249] op_sel_hi:[1,0] neg_lo:[0,1] neg_hi:[0,1]
	v_pk_add_f32 v[98:99], v[98:99], v[248:249] op_sel_hi:[1,0] neg_lo:[0,1] neg_hi:[0,1]
	v_pk_mul_f32 v[92:93], v[92:93], v[254:255] op_sel_hi:[1,0]
	v_pk_mul_f32 v[94:95], v[94:95], v[254:255] op_sel_hi:[1,0]
	v_pk_mul_f32 v[96:97], v[96:97], v[254:255] op_sel_hi:[1,0]
	v_pk_mul_f32 v[98:99], v[98:99], v[254:255] op_sel_hi:[1,0]
	v_exp_f32_e32 v92, v92
	v_exp_f32_e32 v93, v93
	v_exp_f32_e32 v94, v94
	v_exp_f32_e32 v95, v95
	v_exp_f32_e32 v96, v96
	v_exp_f32_e32 v97, v97
	v_exp_f32_e32 v98, v98
	v_exp_f32_e32 v99, v99
	s_nop 0
	v_pk_add_f32 v[2:3], v[2:3], v[92:93]
	v_pk_add_f32 v[2:3], v[2:3], v[94:95]
	v_pk_add_f32 v[2:3], v[2:3], v[96:97]
	v_pk_add_f32 v[2:3], v[2:3], v[98:99]
	v_pk_add_f32 v[100:101], v[100:101], v[248:249] op_sel_hi:[1,0] neg_lo:[0,1] neg_hi:[0,1]
	v_pk_add_f32 v[102:103], v[102:103], v[248:249] op_sel_hi:[1,0] neg_lo:[0,1] neg_hi:[0,1]
	v_pk_add_f32 v[104:105], v[104:105], v[248:249] op_sel_hi:[1,0] neg_lo:[0,1] neg_hi:[0,1]
	v_pk_add_f32 v[106:107], v[106:107], v[248:249] op_sel_hi:[1,0] neg_lo:[0,1] neg_hi:[0,1]
	v_pk_mul_f32 v[100:101], v[100:101], v[254:255] op_sel_hi:[1,0]
	v_pk_mul_f32 v[102:103], v[102:103], v[254:255] op_sel_hi:[1,0]
	v_pk_mul_f32 v[104:105], v[104:105], v[254:255] op_sel_hi:[1,0]
	v_pk_mul_f32 v[106:107], v[106:107], v[254:255] op_sel_hi:[1,0]
	v_exp_f32_e32 v100, v100
	v_exp_f32_e32 v101, v101
	v_exp_f32_e32 v102, v102
	v_exp_f32_e32 v103, v103
	v_exp_f32_e32 v104, v104
	v_exp_f32_e32 v105, v105
	v_exp_f32_e32 v106, v106
	v_exp_f32_e32 v107, v107
	s_nop 0
	v_pk_add_f32 v[2:3], v[2:3], v[100:101]
	v_pk_add_f32 v[2:3], v[2:3], v[102:103]
	v_pk_add_f32 v[2:3], v[2:3], v[104:105]
	v_pk_add_f32 v[2:3], v[2:3], v[106:107]
	v_pk_add_f32 v[108:109], v[108:109], v[248:249] op_sel_hi:[1,0] neg_lo:[0,1] neg_hi:[0,1]
	v_pk_add_f32 v[110:111], v[110:111], v[248:249] op_sel_hi:[1,0] neg_lo:[0,1] neg_hi:[0,1]
	v_pk_add_f32 v[112:113], v[112:113], v[248:249] op_sel_hi:[1,0] neg_lo:[0,1] neg_hi:[0,1]
	v_pk_add_f32 v[114:115], v[114:115], v[248:249] op_sel_hi:[1,0] neg_lo:[0,1] neg_hi:[0,1]
	v_pk_mul_f32 v[108:109], v[108:109], v[254:255] op_sel_hi:[1,0]
	v_pk_mul_f32 v[110:111], v[110:111], v[254:255] op_sel_hi:[1,0]
	v_pk_mul_f32 v[112:113], v[112:113], v[254:255] op_sel_hi:[1,0]
	v_pk_mul_f32 v[114:115], v[114:115], v[254:255] op_sel_hi:[1,0]
	v_exp_f32_e32 v108, v108
	v_exp_f32_e32 v109, v109
	v_exp_f32_e32 v110, v110
	v_exp_f32_e32 v111, v111
	v_exp_f32_e32 v112, v112
	v_exp_f32_e32 v113, v113
	v_exp_f32_e32 v114, v114
	v_exp_f32_e32 v115, v115
	s_nop 0
	v_pk_add_f32 v[2:3], v[2:3], v[108:109]
	v_pk_add_f32 v[2:3], v[2:3], v[110:111]
	v_pk_add_f32 v[2:3], v[2:3], v[112:113]
	v_pk_add_f32 v[2:3], v[2:3], v[114:115]
	v_pk_add_f32 v[116:117], v[116:117], v[248:249] op_sel_hi:[1,0] neg_lo:[0,1] neg_hi:[0,1]
	v_pk_add_f32 v[118:119], v[118:119], v[248:249] op_sel_hi:[1,0] neg_lo:[0,1] neg_hi:[0,1]
	v_pk_add_f32 v[120:121], v[120:121], v[248:249] op_sel_hi:[1,0] neg_lo:[0,1] neg_hi:[0,1]
	v_pk_add_f32 v[122:123], v[122:123], v[248:249] op_sel_hi:[1,0] neg_lo:[0,1] neg_hi:[0,1]
	v_pk_mul_f32 v[116:117], v[116:117], v[254:255] op_sel_hi:[1,0]
	v_pk_mul_f32 v[118:119], v[118:119], v[254:255] op_sel_hi:[1,0]
	v_pk_mul_f32 v[120:121], v[120:121], v[254:255] op_sel_hi:[1,0]
	v_pk_mul_f32 v[122:123], v[122:123], v[254:255] op_sel_hi:[1,0]
	v_exp_f32_e32 v116, v116
	v_exp_f32_e32 v117, v117
	v_exp_f32_e32 v118, v118
	v_exp_f32_e32 v119, v119
	v_exp_f32_e32 v120, v120
	v_exp_f32_e32 v121, v121
	v_exp_f32_e32 v122, v122
	v_exp_f32_e32 v123, v123
	s_nop 0
	v_pk_add_f32 v[2:3], v[2:3], v[116:117]
	v_pk_add_f32 v[2:3], v[2:3], v[118:119]
	v_pk_add_f32 v[2:3], v[2:3], v[120:121]
	v_pk_add_f32 v[2:3], v[2:3], v[122:123]
	v_pk_add_f32 v[124:125], v[124:125], v[248:249] op_sel_hi:[1,0] neg_lo:[0,1] neg_hi:[0,1]
	v_pk_add_f32 v[126:127], v[126:127], v[248:249] op_sel_hi:[1,0] neg_lo:[0,1] neg_hi:[0,1]
	v_pk_add_f32 v[128:129], v[128:129], v[248:249] op_sel_hi:[1,0] neg_lo:[0,1] neg_hi:[0,1]
	v_pk_add_f32 v[130:131], v[130:131], v[248:249] op_sel_hi:[1,0] neg_lo:[0,1] neg_hi:[0,1]
	v_pk_mul_f32 v[124:125], v[124:125], v[254:255] op_sel_hi:[1,0]
	v_pk_mul_f32 v[126:127], v[126:127], v[254:255] op_sel_hi:[1,0]
	v_pk_mul_f32 v[128:129], v[128:129], v[254:255] op_sel_hi:[1,0]
	v_pk_mul_f32 v[130:131], v[130:131], v[254:255] op_sel_hi:[1,0]
	v_exp_f32_e32 v124, v124
	v_exp_f32_e32 v125, v125
	v_exp_f32_e32 v126, v126
	v_exp_f32_e32 v127, v127
	v_exp_f32_e32 v128, v128
	v_exp_f32_e32 v129, v129
	v_exp_f32_e32 v130, v130
	v_exp_f32_e32 v131, v131
	s_nop 0
	v_pk_add_f32 v[2:3], v[2:3], v[124:125]
	v_pk_add_f32 v[2:3], v[2:3], v[126:127]
	v_pk_add_f32 v[2:3], v[2:3], v[128:129]
	v_pk_add_f32 v[2:3], v[2:3], v[130:131]
	v_pk_add_f32 v[132:133], v[132:133], v[248:249] op_sel_hi:[1,0] neg_lo:[0,1] neg_hi:[0,1]
	v_pk_add_f32 v[134:135], v[134:135], v[248:249] op_sel_hi:[1,0] neg_lo:[0,1] neg_hi:[0,1]
	v_pk_add_f32 v[136:137], v[136:137], v[248:249] op_sel_hi:[1,0] neg_lo:[0,1] neg_hi:[0,1]
	v_pk_add_f32 v[138:139], v[138:139], v[248:249] op_sel_hi:[1,0] neg_lo:[0,1] neg_hi:[0,1]
	v_pk_mul_f32 v[132:133], v[132:133], v[254:255] op_sel_hi:[1,0]
	v_pk_mul_f32 v[134:135], v[134:135], v[254:255] op_sel_hi:[1,0]
	v_pk_mul_f32 v[136:137], v[136:137], v[254:255] op_sel_hi:[1,0]
	v_pk_mul_f32 v[138:139], v[138:139], v[254:255] op_sel_hi:[1,0]
	v_exp_f32_e32 v132, v132
	v_exp_f32_e32 v133, v133
	v_exp_f32_e32 v134, v134
	v_exp_f32_e32 v135, v135
	v_exp_f32_e32 v136, v136
	v_exp_f32_e32 v137, v137
	v_exp_f32_e32 v138, v138
	v_exp_f32_e32 v139, v139
	s_nop 0
	v_pk_add_f32 v[2:3], v[2:3], v[132:133]
	v_pk_add_f32 v[2:3], v[2:3], v[134:135]
	v_pk_add_f32 v[2:3], v[2:3], v[136:137]
	v_pk_add_f32 v[2:3], v[2:3], v[138:139]
	v_pk_add_f32 v[140:141], v[140:141], v[248:249] op_sel_hi:[1,0] neg_lo:[0,1] neg_hi:[0,1]
	v_pk_add_f32 v[142:143], v[142:143], v[248:249] op_sel_hi:[1,0] neg_lo:[0,1] neg_hi:[0,1]
	v_pk_add_f32 v[144:145], v[144:145], v[248:249] op_sel_hi:[1,0] neg_lo:[0,1] neg_hi:[0,1]
	v_pk_add_f32 v[146:147], v[146:147], v[248:249] op_sel_hi:[1,0] neg_lo:[0,1] neg_hi:[0,1]
	v_pk_mul_f32 v[140:141], v[140:141], v[254:255] op_sel_hi:[1,0]
	v_pk_mul_f32 v[142:143], v[142:143], v[254:255] op_sel_hi:[1,0]
	v_pk_mul_f32 v[144:145], v[144:145], v[254:255] op_sel_hi:[1,0]
	v_pk_mul_f32 v[146:147], v[146:147], v[254:255] op_sel_hi:[1,0]
	v_exp_f32_e32 v140, v140
	v_exp_f32_e32 v141, v141
	v_exp_f32_e32 v142, v142
	v_exp_f32_e32 v143, v143
	v_exp_f32_e32 v144, v144
	v_exp_f32_e32 v145, v145
	v_exp_f32_e32 v146, v146
	v_exp_f32_e32 v147, v147
	s_nop 0
	v_pk_add_f32 v[2:3], v[2:3], v[140:141]
	v_pk_add_f32 v[2:3], v[2:3], v[142:143]
	v_pk_add_f32 v[2:3], v[2:3], v[144:145]
	v_pk_add_f32 v[2:3], v[2:3], v[146:147]
	v_pk_add_f32 v[148:149], v[148:149], v[248:249] op_sel_hi:[1,0] neg_lo:[0,1] neg_hi:[0,1]
	v_pk_add_f32 v[150:151], v[150:151], v[248:249] op_sel_hi:[1,0] neg_lo:[0,1] neg_hi:[0,1]
	v_pk_add_f32 v[152:153], v[152:153], v[248:249] op_sel_hi:[1,0] neg_lo:[0,1] neg_hi:[0,1]
	v_pk_add_f32 v[154:155], v[154:155], v[248:249] op_sel_hi:[1,0] neg_lo:[0,1] neg_hi:[0,1]
	v_pk_mul_f32 v[148:149], v[148:149], v[254:255] op_sel_hi:[1,0]
	v_pk_mul_f32 v[150:151], v[150:151], v[254:255] op_sel_hi:[1,0]
	v_pk_mul_f32 v[152:153], v[152:153], v[254:255] op_sel_hi:[1,0]
	v_pk_mul_f32 v[154:155], v[154:155], v[254:255] op_sel_hi:[1,0]
	v_exp_f32_e32 v148, v148
	v_exp_f32_e32 v149, v149
	v_exp_f32_e32 v150, v150
	v_exp_f32_e32 v151, v151
	v_exp_f32_e32 v152, v152
	v_exp_f32_e32 v153, v153
	v_exp_f32_e32 v154, v154
	v_exp_f32_e32 v155, v155
	s_nop 0
	v_pk_add_f32 v[2:3], v[2:3], v[148:149]
	v_pk_add_f32 v[2:3], v[2:3], v[150:151]
	v_pk_add_f32 v[2:3], v[2:3], v[152:153]
	v_pk_add_f32 v[2:3], v[2:3], v[154:155]
	v_add_f32_e32 v249, v2, v3
	ds_bpermute_b32 v0, v238, v249
	s_waitcnt lgkmcnt(0)
	v_add_f32_e32 v249, v249, v0
	ds_bpermute_b32 v0, v239, v249
	s_waitcnt lgkmcnt(0)
	v_add_f32_e32 v249, v249, v0
	s_barrier
	s_add_i32 s30, s20, s46
	s_cmpk_lt_i32 s30, 0x200
	s_cbranch_scc0 .Latt_nopf1
	s_and_b32 s69, s30, 7
	s_lshr_b32 s76, s30, 8
	s_lshl_b32 s69, s69, 1
	s_add_i32 s69, s69, s76
	s_lshl_b32 s69, s69, 12
	s_bfe_u32 s76, s30, 0x50003
	s_lshl_b32 s76, s76, 1
	s_add_i32 s77, s76, -4
	s_max_i32 s77, s77, 0
	s_min_i32 s77, s77, 56
	s_add_i32 s83, s76, -3
	s_max_i32 s83, s83, 0
	s_min_i32 s83, s83, 56
	s_add_i32 s83, s83, 8
	s_sub_i32 s83, s83, s77
	s_add_i32 s76, s76, s88
	s_lshl_b32 s77, s77, 6
	s_add_i32 s77, s77, s69
	s_lshl_b32 s77, s77, 8
	s_add_u32 s34, s50, s77
	s_addc_u32 s35, s51, 0
	s_add_u32 s34, s34, 0xe200000
	s_addc_u32 s35, s35, 0
	s_lshl_b32 s76, s76, 6
	s_add_i32 s76, s76, s69
	s_lshl_b32 s77, s92, 4
	s_add_i32 s76, s76, s77
	s_lshl_b32 s76, s76, 8
	s_add_u32 s36, s50, s76
	s_addc_u32 s37, s51, 0
	s_add_u32 s36, s36, 0xd200000
	s_addc_u32 s37, s37, 0
	global_load_dwordx4 v[76:79], v235, s[36:37] offset:0
	global_load_dwordx4 v[80:83], v235, s[36:37] offset:64
	global_load_dwordx4 v[84:87], v235, s[36:37] offset:128
	global_load_dwordx4 v[88:91], v235, s[36:37] offset:192
	global_load_dwordx4 v[4:7], v226, s[34:35]
	global_load_dwordx4 v[8:11], v227, s[34:35]
	s_add_u32 s34, s34, 0x4000
	s_addc_u32 s35, s35, 0
	global_load_dwordx4 v[12:15], v226, s[34:35]
	global_load_dwordx4 v[16:19], v227, s[34:35]
	s_add_u32 s34, s34, 0x4000
	s_addc_u32 s35, s35, 0
	global_load_dwordx4 v[20:23], v226, s[34:35]
	global_load_dwordx4 v[24:27], v227, s[34:35]
	s_add_u32 s34, s34, 0x4000
	s_addc_u32 s35, s35, 0
	global_load_dwordx4 v[28:31], v226, s[34:35]
	global_load_dwordx4 v[32:35], v227, s[34:35]
	s_add_u32 s34, s34, 0x4000
	s_addc_u32 s35, s35, 0
	global_load_dwordx4 v[36:39], v226, s[34:35]
	global_load_dwordx4 v[40:43], v227, s[34:35]
	s_add_u32 s34, s34, 0x4000
	s_addc_u32 s35, s35, 0
	global_load_dwordx4 v[44:47], v226, s[34:35]
	global_load_dwordx4 v[48:51], v227, s[34:35]
	s_add_u32 s34, s34, 0x4000
	s_addc_u32 s35, s35, 0
	global_load_dwordx4 v[52:55], v226, s[34:35]
	global_load_dwordx4 v[56:59], v227, s[34:35]
	s_add_u32 s34, s34, 0x4000
	s_addc_u32 s35, s35, 0
.Latt_nopf1:
	v_cvt_pk_bf16_f32 v220, v92, v93
	v_cvt_pk_bf16_f32 v221, v94, v95
	v_cvt_pk_bf16_f32 v222, v96, v97
	v_cvt_pk_bf16_f32 v223, v98, v99
	s_add_i32 s30, s27, 0
	s_add_i32 s31, s30, -7
	s_cmp_lt_i32 s30, 7
	s_cselect_b32 s30, s30, s31
	s_mul_i32 s30, s30, 0x4800
	s_add_i32 s30, s30, 0x3c00
	v_add_u32_e32 v0, s30, v233
	ds_read_b128 v[156:159], v0 offset:0
	ds_read_b128 v[160:163], v0 offset:2304
	ds_read_b128 v[164:167], v0 offset:4608
	ds_read_b128 v[168:171], v0 offset:6912
	ds_read_b128 v[172:175], v0 offset:9216
	ds_read_b128 v[176:179], v0 offset:11520
	ds_read_b128 v[180:183], v0 offset:13824
	ds_read_b128 v[184:187], v0 offset:16128
	s_waitcnt lgkmcnt(7)
	v_mfma_f32_16x16x32_bf16 v[188:191], v[156:159], v[220:223], 0
	s_waitcnt lgkmcnt(6)
	v_mfma_f32_16x16x32_bf16 v[192:195], v[160:163], v[220:223], 0
	s_waitcnt lgkmcnt(5)
	v_mfma_f32_16x16x32_bf16 v[196:199], v[164:167], v[220:223], 0
	s_waitcnt lgkmcnt(4)
	v_mfma_f32_16x16x32_bf16 v[200:203], v[168:171], v[220:223], 0
	s_waitcnt lgkmcnt(3)
	v_mfma_f32_16x16x32_bf16 v[204:207], v[172:175], v[220:223], 0
	s_waitcnt lgkmcnt(2)
	v_mfma_f32_16x16x32_bf16 v[208:211], v[176:179], v[220:223], 0
	s_waitcnt lgkmcnt(1)
	v_mfma_f32_16x16x32_bf16 v[212:215], v[180:183], v[220:223], 0
	s_waitcnt lgkmcnt(0)
	v_mfma_f32_16x16x32_bf16 v[216:219], v[184:187], v[220:223], 0
	v_cvt_pk_bf16_f32 v220, v100, v101
	v_cvt_pk_bf16_f32 v221, v102, v103
	v_cvt_pk_bf16_f32 v222, v104, v105
	v_cvt_pk_bf16_f32 v223, v106, v107
	s_add_i32 s30, s27, 1
	s_add_i32 s31, s30, -7
	s_cmp_lt_i32 s30, 7
	s_cselect_b32 s30, s30, s31
	s_mul_i32 s30, s30, 0x4800
	s_add_i32 s30, s30, 0x3c00
	v_add_u32_e32 v0, s30, v233
	ds_read_b128 v[156:159], v0 offset:0
	ds_read_b128 v[160:163], v0 offset:2304
	ds_read_b128 v[164:167], v0 offset:4608
	ds_read_b128 v[168:171], v0 offset:6912
	ds_read_b128 v[172:175], v0 offset:9216
	ds_read_b128 v[176:179], v0 offset:11520
	ds_read_b128 v[180:183], v0 offset:13824
	ds_read_b128 v[184:187], v0 offset:16128
	s_waitcnt lgkmcnt(7)
	v_mfma_f32_16x16x32_bf16 v[188:191], v[156:159], v[220:223], v[188:191]
	s_waitcnt lgkmcnt(6)
	v_mfma_f32_16x16x32_bf16 v[192:195], v[160:163], v[220:223], v[192:195]
	s_waitcnt lgkmcnt(5)
	v_mfma_f32_16x16x32_bf16 v[196:199], v[164:167], v[220:223], v[196:199]
	s_waitcnt lgkmcnt(4)
	v_mfma_f32_16x16x32_bf16 v[200:203], v[168:171], v[220:223], v[200:203]
	s_waitcnt lgkmcnt(3)
	v_mfma_f32_16x16x32_bf16 v[204:207], v[172:175], v[220:223], v[204:207]
	s_waitcnt lgkmcnt(2)
	v_mfma_f32_16x16x32_bf16 v[208:211], v[176:179], v[220:223], v[208:211]
	s_waitcnt lgkmcnt(1)
	v_mfma_f32_16x16x32_bf16 v[212:215], v[180:183], v[220:223], v[212:215]
	s_waitcnt lgkmcnt(0)
	v_mfma_f32_16x16x32_bf16 v[216:219], v[184:187], v[220:223], v[216:219]
	v_cvt_pk_bf16_f32 v220, v108, v109
	v_cvt_pk_bf16_f32 v221, v110, v111
	v_cvt_pk_bf16_f32 v222, v112, v113
	v_cvt_pk_bf16_f32 v223, v114, v115
	s_add_i32 s30, s27, 2
	s_add_i32 s31, s30, -7
	s_cmp_lt_i32 s30, 7
	s_cselect_b32 s30, s30, s31
	s_mul_i32 s30, s30, 0x4800
	s_add_i32 s30, s30, 0x3c00
	v_add_u32_e32 v0, s30, v233
	ds_read_b128 v[156:159], v0 offset:0
	ds_read_b128 v[160:163], v0 offset:2304
	ds_read_b128 v[164:167], v0 offset:4608
	ds_read_b128 v[168:171], v0 offset:6912
	ds_read_b128 v[172:175], v0 offset:9216
	ds_read_b128 v[176:179], v0 offset:11520
	ds_read_b128 v[180:183], v0 offset:13824
	ds_read_b128 v[184:187], v0 offset:16128
	s_waitcnt lgkmcnt(7)
	v_mfma_f32_16x16x32_bf16 v[188:191], v[156:159], v[220:223], v[188:191]
	s_waitcnt lgkmcnt(6)
	v_mfma_f32_16x16x32_bf16 v[192:195], v[160:163], v[220:223], v[192:195]
	s_waitcnt lgkmcnt(5)
	v_mfma_f32_16x16x32_bf16 v[196:199], v[164:167], v[220:223], v[196:199]
	s_waitcnt lgkmcnt(4)
	v_mfma_f32_16x16x32_bf16 v[200:203], v[168:171], v[220:223], v[200:203]
	s_waitcnt lgkmcnt(3)
	v_mfma_f32_16x16x32_bf16 v[204:207], v[172:175], v[220:223], v[204:207]
	s_waitcnt lgkmcnt(2)
	v_mfma_f32_16x16x32_bf16 v[208:211], v[176:179], v[220:223], v[208:211]
	s_waitcnt lgkmcnt(1)
	v_mfma_f32_16x16x32_bf16 v[212:215], v[180:183], v[220:223], v[212:215]
	s_waitcnt lgkmcnt(0)
	v_mfma_f32_16x16x32_bf16 v[216:219], v[184:187], v[220:223], v[216:219]
	v_cvt_pk_bf16_f32 v220, v116, v117
	v_cvt_pk_bf16_f32 v221, v118, v119
	v_cvt_pk_bf16_f32 v222, v120, v121
	v_cvt_pk_bf16_f32 v223, v122, v123
	s_add_i32 s30, s27, 3
	s_add_i32 s31, s30, -7
	s_cmp_lt_i32 s30, 7
	s_cselect_b32 s30, s30, s31
	s_mul_i32 s30, s30, 0x4800
	s_add_i32 s30, s30, 0x3c00
	v_add_u32_e32 v0, s30, v233
	ds_read_b128 v[156:159], v0 offset:0
	ds_read_b128 v[160:163], v0 offset:2304
	ds_read_b128 v[164:167], v0 offset:4608
	ds_read_b128 v[168:171], v0 offset:6912
	ds_read_b128 v[172:175], v0 offset:9216
	ds_read_b128 v[176:179], v0 offset:11520
	ds_read_b128 v[180:183], v0 offset:13824
	ds_read_b128 v[184:187], v0 offset:16128
	s_waitcnt lgkmcnt(7)
	v_mfma_f32_16x16x32_bf16 v[188:191], v[156:159], v[220:223], v[188:191]
	s_waitcnt lgkmcnt(6)
	v_mfma_f32_16x16x32_bf16 v[192:195], v[160:163], v[220:223], v[192:195]
	s_waitcnt lgkmcnt(5)
	v_mfma_f32_16x16x32_bf16 v[196:199], v[164:167], v[220:223], v[196:199]
	s_waitcnt lgkmcnt(4)
	v_mfma_f32_16x16x32_bf16 v[200:203], v[168:171], v[220:223], v[200:203]
	s_waitcnt lgkmcnt(3)
	v_mfma_f32_16x16x32_bf16 v[204:207], v[172:175], v[220:223], v[204:207]
	s_waitcnt lgkmcnt(2)
	v_mfma_f32_16x16x32_bf16 v[208:211], v[176:179], v[220:223], v[208:211]
	s_waitcnt lgkmcnt(1)
	v_mfma_f32_16x16x32_bf16 v[212:215], v[180:183], v[220:223], v[212:215]
	s_waitcnt lgkmcnt(0)
	v_mfma_f32_16x16x32_bf16 v[216:219], v[184:187], v[220:223], v[216:219]
	global_load_dwordx4 v[92:95], v237, s[60:61] offset:0
	global_load_dwordx4 v[96:99], v237, s[60:61] offset:64
	global_load_dwordx4 v[100:103], v237, s[60:61] offset:128
	global_load_dwordx4 v[104:107], v237, s[60:61] offset:192
	global_load_dwordx4 v[108:111], v237, s[60:61] offset:256
	global_load_dwordx4 v[112:115], v237, s[60:61] offset:320
	global_load_dwordx4 v[116:119], v237, s[60:61] offset:384
	global_load_dwordx4 v[120:123], v237, s[60:61] offset:448
	v_cvt_pk_bf16_f32 v220, v124, v125
	v_cvt_pk_bf16_f32 v221, v126, v127
	v_cvt_pk_bf16_f32 v222, v128, v129
	v_cvt_pk_bf16_f32 v223, v130, v131
	s_add_i32 s30, s27, 4
	s_add_i32 s31, s30, -7
	s_cmp_lt_i32 s30, 7
	s_cselect_b32 s30, s30, s31
	s_mul_i32 s30, s30, 0x4800
	s_add_i32 s30, s30, 0x3c00
	v_add_u32_e32 v0, s30, v233
	ds_read_b128 v[156:159], v0 offset:0
	ds_read_b128 v[160:163], v0 offset:2304
	ds_read_b128 v[164:167], v0 offset:4608
	ds_read_b128 v[168:171], v0 offset:6912
	ds_read_b128 v[172:175], v0 offset:9216
	ds_read_b128 v[176:179], v0 offset:11520
	ds_read_b128 v[180:183], v0 offset:13824
	ds_read_b128 v[184:187], v0 offset:16128
	s_waitcnt lgkmcnt(7)
	v_mfma_f32_16x16x32_bf16 v[188:191], v[156:159], v[220:223], v[188:191]
	s_waitcnt lgkmcnt(6)
	v_mfma_f32_16x16x32_bf16 v[192:195], v[160:163], v[220:223], v[192:195]
	s_waitcnt lgkmcnt(5)
	v_mfma_f32_16x16x32_bf16 v[196:199], v[164:167], v[220:223], v[196:199]
	s_waitcnt lgkmcnt(4)
	v_mfma_f32_16x16x32_bf16 v[200:203], v[168:171], v[220:223], v[200:203]
	s_waitcnt lgkmcnt(3)
	v_mfma_f32_16x16x32_bf16 v[204:207], v[172:175], v[220:223], v[204:207]
	s_waitcnt lgkmcnt(2)
	v_mfma_f32_16x16x32_bf16 v[208:211], v[176:179], v[220:223], v[208:211]
	s_waitcnt lgkmcnt(1)
	v_mfma_f32_16x16x32_bf16 v[212:215], v[180:183], v[220:223], v[212:215]
	s_waitcnt lgkmcnt(0)
	v_mfma_f32_16x16x32_bf16 v[216:219], v[184:187], v[220:223], v[216:219]
	v_cvt_pk_bf16_f32 v220, v132, v133
	v_cvt_pk_bf16_f32 v221, v134, v135
	v_cvt_pk_bf16_f32 v222, v136, v137
	v_cvt_pk_bf16_f32 v223, v138, v139
	s_add_i32 s30, s27, 5
	s_add_i32 s31, s30, -7
	s_cmp_lt_i32 s30, 7
	s_cselect_b32 s30, s30, s31
	s_mul_i32 s30, s30, 0x4800
	s_add_i32 s30, s30, 0x3c00
	v_add_u32_e32 v0, s30, v233
	ds_read_b128 v[156:159], v0 offset:0
	ds_read_b128 v[160:163], v0 offset:2304
	ds_read_b128 v[164:167], v0 offset:4608
	ds_read_b128 v[168:171], v0 offset:6912
	ds_read_b128 v[172:175], v0 offset:9216
	ds_read_b128 v[176:179], v0 offset:11520
	ds_read_b128 v[180:183], v0 offset:13824
	ds_read_b128 v[184:187], v0 offset:16128
	s_waitcnt lgkmcnt(7)
	v_mfma_f32_16x16x32_bf16 v[188:191], v[156:159], v[220:223], v[188:191]
	s_waitcnt lgkmcnt(6)
	v_mfma_f32_16x16x32_bf16 v[192:195], v[160:163], v[220:223], v[192:195]
	s_waitcnt lgkmcnt(5)
	v_mfma_f32_16x16x32_bf16 v[196:199], v[164:167], v[220:223], v[196:199]
	s_waitcnt lgkmcnt(4)
	v_mfma_f32_16x16x32_bf16 v[200:203], v[168:171], v[220:223], v[200:203]
	s_waitcnt lgkmcnt(3)
	v_mfma_f32_16x16x32_bf16 v[204:207], v[172:175], v[220:223], v[204:207]
	s_waitcnt lgkmcnt(2)
	v_mfma_f32_16x16x32_bf16 v[208:211], v[176:179], v[220:223], v[208:211]
	s_waitcnt lgkmcnt(1)
	v_mfma_f32_16x16x32_bf16 v[212:215], v[180:183], v[220:223], v[212:215]
	s_waitcnt lgkmcnt(0)
	v_mfma_f32_16x16x32_bf16 v[216:219], v[184:187], v[220:223], v[216:219]
	s_cmp_lg_u32 s27, 0
	s_cbranch_scc1 .Latt_p6a_skip
	v_cvt_pk_bf16_f32 v220, v140, v141
	v_cvt_pk_bf16_f32 v221, v142, v143
	v_cvt_pk_bf16_f32 v222, v144, v145
	v_cvt_pk_bf16_f32 v223, v146, v147
	s_add_i32 s30, s27, 6
	s_add_i32 s31, s30, -7
	s_cmp_lt_i32 s30, 7
	s_cselect_b32 s30, s30, s31
	s_mul_i32 s30, s30, 0x4800
	s_add_i32 s30, s30, 0x3c00
	v_add_u32_e32 v0, s30, v233
	ds_read_b128 v[156:159], v0 offset:0
	ds_read_b128 v[160:163], v0 offset:2304
	ds_read_b128 v[164:167], v0 offset:4608
	ds_read_b128 v[168:171], v0 offset:6912
	ds_read_b128 v[172:175], v0 offset:9216
	ds_read_b128 v[176:179], v0 offset:11520
	ds_read_b128 v[180:183], v0 offset:13824
	ds_read_b128 v[184:187], v0 offset:16128
	s_waitcnt lgkmcnt(7)
	v_mfma_f32_16x16x32_bf16 v[188:191], v[156:159], v[220:223], v[188:191]
	s_waitcnt lgkmcnt(6)
	v_mfma_f32_16x16x32_bf16 v[192:195], v[160:163], v[220:223], v[192:195]
	s_waitcnt lgkmcnt(5)
	v_mfma_f32_16x16x32_bf16 v[196:199], v[164:167], v[220:223], v[196:199]
	s_waitcnt lgkmcnt(4)
	v_mfma_f32_16x16x32_bf16 v[200:203], v[168:171], v[220:223], v[200:203]
	s_waitcnt lgkmcnt(3)
	v_mfma_f32_16x16x32_bf16 v[204:207], v[172:175], v[220:223], v[204:207]
	s_waitcnt lgkmcnt(2)
	v_mfma_f32_16x16x32_bf16 v[208:211], v[176:179], v[220:223], v[208:211]
	s_waitcnt lgkmcnt(1)
	v_mfma_f32_16x16x32_bf16 v[212:215], v[180:183], v[220:223], v[212:215]
	s_waitcnt lgkmcnt(0)
	v_mfma_f32_16x16x32_bf16 v[216:219], v[184:187], v[220:223], v[216:219]
.Latt_p6a_skip:
	s_barrier
	s_add_i32 s30, s20, s46
	s_cmpk_lt_i32 s30, 0x200
	s_cbranch_scc0 .Latt_nopf2
	s_waitcnt vmcnt(26)
	s_branch .Latt_vw78

.Latt_vw78:
	v_add_u32_e32 v0, 0x3c00, v231
	ds_write_b128 v0, v[60:63]
	ds_write_b128 v0, v[64:67] offset:9216
	s_cmp_lt_u32 s28, 9
	s_cbranch_scc1 .Latt_vw8_skip
	v_add_u32_e32 v0, 0x8400, v231
	ds_write_b128 v0, v[68:71]
	ds_write_b128 v0, v[72:75] offset:9216
.Latt_vw8_skip:
	s_waitcnt lgkmcnt(0)
	s_barrier
	s_add_i32 s30, s20, s46
	s_cmpk_lt_i32 s30, 0x200
	s_cbranch_scc0 .Latt_nopf3
	global_load_dwordx4 v[60:63], v226, s[34:35]
	global_load_dwordx4 v[64:67], v227, s[34:35]
	s_add_u32 s34, s34, 0x4000
	s_addc_u32 s35, s35, 0
	s_cmp_lt_u32 s83, 9
	s_cbranch_scc1 .Latt_k8_skip_g
	global_load_dwordx4 v[68:71], v226, s[34:35]
	global_load_dwordx4 v[72:75], v227, s[34:35]
.Latt_k8_skip_g:
.Latt_nopf3:
	s_cmp_eq_u32 s27, 0
	s_cbranch_scc1 .Latt_p6b_skip
	v_cvt_pk_bf16_f32 v220, v140, v141
	v_cvt_pk_bf16_f32 v221, v142, v143
	v_cvt_pk_bf16_f32 v222, v144, v145
	v_cvt_pk_bf16_f32 v223, v146, v147
	s_add_i32 s30, s27, 6
	s_add_i32 s31, s30, -7
	s_cmp_lt_i32 s30, 7
	s_cselect_b32 s30, s30, s31
	s_mul_i32 s30, s30, 0x4800
	s_add_i32 s30, s30, 0x3c00
	v_add_u32_e32 v0, s30, v233
	ds_read_b128 v[156:159], v0 offset:0
	ds_read_b128 v[160:163], v0 offset:2304
	ds_read_b128 v[164:167], v0 offset:4608
	ds_read_b128 v[168:171], v0 offset:6912
	ds_read_b128 v[172:175], v0 offset:9216
	ds_read_b128 v[176:179], v0 offset:11520
	ds_read_b128 v[180:183], v0 offset:13824
	ds_read_b128 v[184:187], v0 offset:16128
	s_waitcnt lgkmcnt(7)
	v_mfma_f32_16x16x32_bf16 v[188:191], v[156:159], v[220:223], v[188:191]
	s_waitcnt lgkmcnt(6)
	v_mfma_f32_16x16x32_bf16 v[192:195], v[160:163], v[220:223], v[192:195]
	s_waitcnt lgkmcnt(5)
	v_mfma_f32_16x16x32_bf16 v[196:199], v[164:167], v[220:223], v[196:199]
	s_waitcnt lgkmcnt(4)
	v_mfma_f32_16x16x32_bf16 v[200:203], v[168:171], v[220:223], v[200:203]
	s_waitcnt lgkmcnt(3)
	v_mfma_f32_16x16x32_bf16 v[204:207], v[172:175], v[220:223], v[204:207]
	s_waitcnt lgkmcnt(2)
	v_mfma_f32_16x16x32_bf16 v[208:211], v[176:179], v[220:223], v[208:211]
	s_waitcnt lgkmcnt(1)
	v_mfma_f32_16x16x32_bf16 v[212:215], v[180:183], v[220:223], v[212:215]
	s_waitcnt lgkmcnt(0)
	v_mfma_f32_16x16x32_bf16 v[216:219], v[184:187], v[220:223], v[216:219]
.Latt_p6b_skip:
	v_cvt_pk_bf16_f32 v220, v148, v149
	v_cvt_pk_bf16_f32 v221, v150, v151
	v_cvt_pk_bf16_f32 v222, v152, v153
	v_cvt_pk_bf16_f32 v223, v154, v155
	s_add_i32 s30, s27, 7
	s_add_i32 s31, s30, -7
	s_cmp_lt_i32 s30, 7
	s_cselect_b32 s30, s30, s31
	s_mul_i32 s30, s30, 0x4800
	s_add_i32 s30, s30, 0x3c00
	v_add_u32_e32 v0, s30, v233
	ds_read_b128 v[156:159], v0 offset:0
	ds_read_b128 v[160:163], v0 offset:2304
	ds_read_b128 v[164:167], v0 offset:4608
	ds_read_b128 v[168:171], v0 offset:6912
	ds_read_b128 v[172:175], v0 offset:9216
	ds_read_b128 v[176:179], v0 offset:11520
	ds_read_b128 v[180:183], v0 offset:13824
	ds_read_b128 v[184:187], v0 offset:16128
	s_waitcnt lgkmcnt(7)
	v_mfma_f32_16x16x32_bf16 v[188:191], v[156:159], v[220:223], v[188:191]
	s_waitcnt lgkmcnt(6)
	v_mfma_f32_16x16x32_bf16 v[192:195], v[160:163], v[220:223], v[192:195]
	s_waitcnt lgkmcnt(5)
	v_mfma_f32_16x16x32_bf16 v[196:199], v[164:167], v[220:223], v[196:199]
	s_waitcnt lgkmcnt(4)
	v_mfma_f32_16x16x32_bf16 v[200:203], v[168:171], v[220:223], v[200:203]
	s_waitcnt lgkmcnt(3)
	v_mfma_f32_16x16x32_bf16 v[204:207], v[172:175], v[220:223], v[204:207]
	s_waitcnt lgkmcnt(2)
	v_mfma_f32_16x16x32_bf16 v[208:211], v[176:179], v[220:223], v[208:211]
	s_waitcnt lgkmcnt(1)
	v_mfma_f32_16x16x32_bf16 v[212:215], v[180:183], v[220:223], v[212:215]
	s_waitcnt lgkmcnt(0)
	v_mfma_f32_16x16x32_bf16 v[216:219], v[184:187], v[220:223], v[216:219]
	v_div_scale_f32 v252, s[44:45], v249, v249, 1.0
	v_rcp_f32_e32 v253, v252
	v_div_scale_f32 v254, vcc, 1.0, v249, 1.0
	s_nop 0
	v_fma_f32 v255, -v252, v253, 1.0
	v_fmac_f32_e32 v253, v255, v253
	v_mul_f32_e32 v255, v254, v253
	v_fma_f32 v248, -v252, v255, v254
	v_fmac_f32_e32 v255, v248, v253
	v_fma_f32 v252, -v252, v255, v254
	v_div_fmas_f32 v252, v252, v253, v255
	v_div_fixup_f32 v252, v252, v249, 1.0
	s_nop 7
	v_pk_mul_f32 v[188:189], v[188:189], v[252:253] op_sel_hi:[1,0]
	v_pk_mul_f32 v[190:191], v[190:191], v[252:253] op_sel_hi:[1,0]
	v_pk_mul_f32 v[192:193], v[192:193], v[252:253] op_sel_hi:[1,0]
	v_pk_mul_f32 v[194:195], v[194:195], v[252:253] op_sel_hi:[1,0]
	v_pk_mul_f32 v[196:197], v[196:197], v[252:253] op_sel_hi:[1,0]
	v_pk_mul_f32 v[198:199], v[198:199], v[252:253] op_sel_hi:[1,0]
	v_pk_mul_f32 v[200:201], v[200:201], v[252:253] op_sel_hi:[1,0]
	v_pk_mul_f32 v[202:203], v[202:203], v[252:253] op_sel_hi:[1,0]
	v_pk_mul_f32 v[204:205], v[204:205], v[252:253] op_sel_hi:[1,0]
	v_pk_mul_f32 v[206:207], v[206:207], v[252:253] op_sel_hi:[1,0]
	v_pk_mul_f32 v[208:209], v[208:209], v[252:253] op_sel_hi:[1,0]
	v_pk_mul_f32 v[210:211], v[210:211], v[252:253] op_sel_hi:[1,0]
	v_pk_mul_f32 v[212:213], v[212:213], v[252:253] op_sel_hi:[1,0]
	v_pk_mul_f32 v[214:215], v[214:215], v[252:253] op_sel_hi:[1,0]
	v_pk_mul_f32 v[216:217], v[216:217], v[252:253] op_sel_hi:[1,0]
	v_pk_mul_f32 v[218:219], v[218:219], v[252:253] op_sel_hi:[1,0]
	v_pk_mul_f32 v[254:255], v[188:189], v[188:189]
	v_pk_fma_f32 v[254:255], v[190:191], v[190:191], v[254:255]
	v_pk_fma_f32 v[254:255], v[192:193], v[192:193], v[254:255]
	v_pk_fma_f32 v[254:255], v[194:195], v[194:195], v[254:255]
	v_pk_fma_f32 v[254:255], v[196:197], v[196:197], v[254:255]
	v_pk_fma_f32 v[254:255], v[198:199], v[198:199], v[254:255]
	v_pk_fma_f32 v[254:255], v[200:201], v[200:201], v[254:255]
	v_pk_fma_f32 v[254:255], v[202:203], v[202:203], v[254:255]
	v_pk_fma_f32 v[254:255], v[204:205], v[204:205], v[254:255]
	v_pk_fma_f32 v[254:255], v[206:207], v[206:207], v[254:255]
	v_pk_fma_f32 v[254:255], v[208:209], v[208:209], v[254:255]
	v_pk_fma_f32 v[254:255], v[210:211], v[210:211], v[254:255]
	v_pk_fma_f32 v[254:255], v[212:213], v[212:213], v[254:255]
	v_pk_fma_f32 v[254:255], v[214:215], v[214:215], v[254:255]
	v_pk_fma_f32 v[254:255], v[216:217], v[216:217], v[254:255]
	v_pk_fma_f32 v[254:255], v[218:219], v[218:219], v[254:255]
	v_add_f32_e32 v254, v254, v255
	ds_bpermute_b32 v253, v238, v254
	s_waitcnt lgkmcnt(0)
	v_add_f32_e32 v254, v254, v253
	ds_bpermute_b32 v253, v239, v254
	s_waitcnt lgkmcnt(0)
	v_add_f32_e32 v254, v254, v253
	v_mov_b32_e32 v253, 0x358637bd
	s_mov_b32 s30, 0x800000
	v_fmamk_f32 v254, v254, 0x3c000000, v253
	v_mul_f32_e32 v253, 0x4b800000, v254
	v_cmp_gt_f32_e32 vcc, s30, v254
	s_nop 1
	v_cndmask_b32_e32 v254, v254, v253, vcc
	v_rsq_f32_e32 v254, v254
	s_nop 0
	v_mul_f32_e32 v253, 0x45800000, v254
	v_cndmask_b32_e32 v254, v254, v253, vcc
	s_add_i32 s30, s20, s46
	s_cmpk_lt_i32 s30, 0x200
	s_cbranch_scc0 .Latt_nopf4
	s_waitcnt vmcnt(2)
	s_branch .Latt_gn_ok

.Latt_gn_ok:
	v_pk_mul_f32 v[188:189], v[188:189], v[254:255] op_sel_hi:[1,0]
	v_pk_mul_f32 v[190:191], v[190:191], v[254:255] op_sel_hi:[1,0]
	v_pk_mul_f32 v[188:189], v[92:93], v[188:189]
	v_pk_mul_f32 v[190:191], v[94:95], v[190:191]
	v_cvt_pk_bf16_f32 v188, v188, v189
	v_cvt_pk_bf16_f32 v189, v190, v191
	global_store_dwordx2 v236, v[188:189], s[40:41] offset:0
	v_pk_mul_f32 v[192:193], v[192:193], v[254:255] op_sel_hi:[1,0]
	v_pk_mul_f32 v[194:195], v[194:195], v[254:255] op_sel_hi:[1,0]
	v_pk_mul_f32 v[192:193], v[96:97], v[192:193]
	v_pk_mul_f32 v[194:195], v[98:99], v[194:195]
	v_cvt_pk_bf16_f32 v192, v192, v193
	v_cvt_pk_bf16_f32 v193, v194, v195
	global_store_dwordx2 v236, v[192:193], s[40:41] offset:32
	v_pk_mul_f32 v[196:197], v[196:197], v[254:255] op_sel_hi:[1,0]
	v_pk_mul_f32 v[198:199], v[198:199], v[254:255] op_sel_hi:[1,0]
	v_pk_mul_f32 v[196:197], v[100:101], v[196:197]
	v_pk_mul_f32 v[198:199], v[102:103], v[198:199]
	v_cvt_pk_bf16_f32 v196, v196, v197
	v_cvt_pk_bf16_f32 v197, v198, v199
	global_store_dwordx2 v236, v[196:197], s[40:41] offset:64
	v_pk_mul_f32 v[200:201], v[200:201], v[254:255] op_sel_hi:[1,0]
	v_pk_mul_f32 v[202:203], v[202:203], v[254:255] op_sel_hi:[1,0]
	v_pk_mul_f32 v[200:201], v[104:105], v[200:201]
	v_pk_mul_f32 v[202:203], v[106:107], v[202:203]
	v_cvt_pk_bf16_f32 v200, v200, v201
	v_cvt_pk_bf16_f32 v201, v202, v203
	global_store_dwordx2 v236, v[200:201], s[40:41] offset:96
	v_pk_mul_f32 v[204:205], v[204:205], v[254:255] op_sel_hi:[1,0]
	v_pk_mul_f32 v[206:207], v[206:207], v[254:255] op_sel_hi:[1,0]
	v_pk_mul_f32 v[204:205], v[108:109], v[204:205]
	v_pk_mul_f32 v[206:207], v[110:111], v[206:207]
	v_cvt_pk_bf16_f32 v204, v204, v205
	v_cvt_pk_bf16_f32 v205, v206, v207
	global_store_dwordx2 v236, v[204:205], s[40:41] offset:128
	v_pk_mul_f32 v[208:209], v[208:209], v[254:255] op_sel_hi:[1,0]
	v_pk_mul_f32 v[210:211], v[210:211], v[254:255] op_sel_hi:[1,0]
	v_pk_mul_f32 v[208:209], v[112:113], v[208:209]
	v_pk_mul_f32 v[210:211], v[114:115], v[210:211]
	v_cvt_pk_bf16_f32 v208, v208, v209
	v_cvt_pk_bf16_f32 v209, v210, v211
	global_store_dwordx2 v236, v[208:209], s[40:41] offset:160
	v_pk_mul_f32 v[212:213], v[212:213], v[254:255] op_sel_hi:[1,0]
	v_pk_mul_f32 v[214:215], v[214:215], v[254:255] op_sel_hi:[1,0]
	v_pk_mul_f32 v[212:213], v[116:117], v[212:213]
	v_pk_mul_f32 v[214:215], v[118:119], v[214:215]
	v_cvt_pk_bf16_f32 v212, v212, v213
	v_cvt_pk_bf16_f32 v213, v214, v215
	global_store_dwordx2 v236, v[212:213], s[40:41] offset:192
	v_pk_mul_f32 v[216:217], v[216:217], v[254:255] op_sel_hi:[1,0]
	v_pk_mul_f32 v[218:219], v[218:219], v[254:255] op_sel_hi:[1,0]
	v_pk_mul_f32 v[216:217], v[120:121], v[216:217]
	v_pk_mul_f32 v[218:219], v[122:123], v[218:219]
	v_cvt_pk_bf16_f32 v216, v216, v217
	v_cvt_pk_bf16_f32 v217, v218, v219
	global_store_dwordx2 v236, v[216:217], s[40:41] offset:224
	s_barrier
	s_add_i32 s20, s20, s46
	s_cmpk_lt_i32 s20, 0x200
	s_cbranch_scc0 .Latt_done
	s_and_b32 s30, s20, 7
	s_lshr_b32 s31, s20, 8
	s_lshl_b32 s30, s30, 1
	s_add_i32 s30, s30, s31
	s_lshr_b32 s21, s30, 3
	s_and_b32 s22, s30, 7
	s_bfe_u32 s23, s20, 0x50003
	s_lshl_b32 s24, s23, 1
	s_add_i32 s24, s24, s88
	s_lshl_b32 s31, s23, 1
	s_add_i32 s25, s31, -4
	s_max_i32 s25, s25, 0
	s_min_i32 s25, s25, 56
	s_add_i32 s26, s24, -4
	s_max_i32 s26, s26, 0
	s_min_i32 s26, s26, 56
	s_sub_i32 s27, s26, s25
	s_add_i32 s28, s31, -3
	s_max_i32 s28, s28, 0
	s_min_i32 s28, s28, 56
	s_add_i32 s28, s28, 8
	s_sub_i32 s28, s28, s25
	s_lshl_b32 s31, s22, 20
	s_lshl_b32 s30, s21, 12
	s_add_i32 s31, s31, s30
	s_lshl_b32 s30, s25, 6
	s_add_i32 s31, s31, s30
	s_lshl_b32 s31, s31, 1
	s_add_u32 s38, s50, s31
	s_addc_u32 s39, s51, 0
	s_add_u32 s38, s38, 0xf200000
	s_addc_u32 s39, s39, 0
	s_lshl_b32 s31, s21, 12
	s_lshl_b32 s30, s24, 6
	s_add_i32 s31, s31, s30
	s_lshl_b32 s30, s92, 4
	s_add_i32 s31, s31, s30
	s_lshl_b32 s31, s31, 11
	s_lshl_b32 s30, s22, 7
	s_add_i32 s31, s31, s30
	s_lshl_b32 s31, s31, 1
	s_add_u32 s40, s74, s31
	s_addc_u32 s41, s75, 0
	s_lshl_b32 s31, s22, 9
	s_add_u32 s60, s96, s31
	s_addc_u32 s61, s97, 0
	s_sub_i32 s31, s26, s24
	s_add_i32 s31, s31, 7
	s_mul_i32 s31, s31, 31
	s_mul_i32 s67, s22, 465
	s_add_i32 s67, s67, s31
	s_lshl_b32 s67, s67, 2
	v_add_u32_e32 v0, 0x3c00, v228
	ds_write_b128 v0, v[4:7]
	ds_write_b128 v0, v[8:11] offset:8704
	v_add_u32_e32 v0, 0x8400, v228
	ds_write_b128 v0, v[12:15]
	ds_write_b128 v0, v[16:19] offset:8704
	v_add_u32_e32 v0, 0xcc00, v228
	ds_write_b128 v0, v[20:23]
	ds_write_b128 v0, v[24:27] offset:8704
	v_add_u32_e32 v0, 0x11400, v228
	ds_write_b128 v0, v[28:31]
	ds_write_b128 v0, v[32:35] offset:8704
	v_add_u32_e32 v0, 0x15c00, v228
	ds_write_b128 v0, v[36:39]
	ds_write_b128 v0, v[40:43] offset:8704
	v_add_u32_e32 v0, 0x1a400, v228
	ds_write_b128 v0, v[44:47]
	ds_write_b128 v0, v[48:51] offset:8704
	v_add_u32_e32 v0, 0x1ec00, v228
	ds_write_b128 v0, v[52:55]
	ds_write_b128 v0, v[56:59] offset:8704
	s_branch .Latt_unit
.Latt_done:
.LBB0_867:
	s_cmpk_gt_i32 s66, 0x7ff
	s_cbranch_scc1 .LBB0_877
	s_waitcnt vmcnt(15)
	v_mbcnt_hi_u32_b32 v0, -1, v225
	v_and_b32_e32 v2, 64, v0
	v_xor_b32_e32 v1, 1, v0
	v_add_u32_e32 v2, 64, v2
	v_cmp_lt_i32_e32 vcc, v1, v2
	s_load_dwordx4 s[4:7], s[0:1], 0x48
	s_load_dwordx2 s[8:9], s[0:1], 0x60
	v_cndmask_b32_e32 v1, v0, v1, vcc
	v_lshlrev_b32_e32 v97, 2, v1
	v_xor_b32_e32 v1, 2, v0
	v_cmp_lt_i32_e32 vcc, v1, v2
	s_waitcnt lgkmcnt(0)
	s_add_u32 s10, s4, 0x1000
	s_addc_u32 s11, s5, 0
	v_cndmask_b32_e32 v1, v0, v1, vcc
	v_lshlrev_b32_e32 v98, 2, v1
	v_xor_b32_e32 v1, 4, v0
	v_cmp_lt_i32_e32 vcc, v1, v2
	s_add_u32 s12, s4, 0x2000
	s_addc_u32 s13, s5, 0
	v_cndmask_b32_e32 v1, v0, v1, vcc
	v_lshlrev_b32_e32 v99, 2, v1
	v_xor_b32_e32 v1, 8, v0
	v_cmp_lt_i32_e32 vcc, v1, v2
	s_lshl_b32 s14, s2, 5
	s_lshl_b32 s15, s91, 2
	v_cndmask_b32_e32 v0, v0, v1, vcc
	s_add_i32 s18, s14, s15
	s_lshl_b32 s14, s2, 12
	s_lshl_b32 s15, s91, 9
	v_lshlrev_b32_e32 v96, 3, v234
	v_lshlrev_b32_e32 v100, 2, v0
	s_lshl_b32 s19, s46, 5
	s_add_i32 s20, s14, s15
	s_lshl_b32 s21, s46, 12
	s_movk_i32 s22, 0x1000
	s_movk_i32 s23, 0x2000
	v_mov_b32_e32 v101, 0x358637bd
	s_mov_b32 s24, 0x800000
	s_movk_i32 s25, 0x3000
	s_movk_i32 s26, 0x4000
	s_movk_i32 s27, 0x5000
	s_movk_i32 s28, 0x6000
	s_movk_i32 s29, 0x7000
	s_mov_b32 s30, 0x8000
	s_mov_b32 s31, 0x9000
	s_mov_b32 s34, 0xb000
	s_branch .LBB0_870
